# FoX full tiles: lazy running-max with decay bias (cq - M - ck) preloaded into the QK accumulators; hazard pads added in lazy blocks
# speedup vs baseline: 1.0334x; 1.0000x over previous
.Lfoxf_x0:
	s_waitcnt vmcnt(2)
	s_waitcnt lgkmcnt(0)
	v_mfma_f32_16x16x32_bf16 v[208:211], v[64:67], v[96:99], 0
	v_sub_f32_e32 v112, v112, v224
	v_sub_f32_e32 v113, v113, v225
	v_sub_f32_e32 v114, v114, v226
	v_sub_f32_e32 v115, v115, v227
	v_sub_f32_e32 v116, v116, v228
	v_sub_f32_e32 v117, v117, v229
	v_sub_f32_e32 v118, v118, v230
	v_sub_f32_e32 v119, v119, v231
	v_sub_f32_e32 v120, v120, v224
	v_sub_f32_e32 v121, v121, v225
	v_sub_f32_e32 v122, v122, v226
	v_sub_f32_e32 v123, v123, v227
	v_mfma_f32_16x16x32_bf16 v[212:215], v[68:71], v[96:99], 0
	v_sub_f32_e32 v124, v124, v228
	v_sub_f32_e32 v125, v125, v229
	v_sub_f32_e32 v126, v126, v230
	v_sub_f32_e32 v127, v127, v231
	v_max3_f32 v240, v112, v113, v114
	v_max3_f32 v240, v240, v115, v116
	v_max3_f32 v240, v240, v117, v118
	v_max_f32_e32 v240, v240, v119
	v_max3_f32 v241, v120, v121, v122
	v_max3_f32 v241, v241, v123, v124
	v_max3_f32 v241, v241, v125, v126
	v_max_f32_e32 v241, v241, v127
	v_mfma_f32_16x16x32_bf16 v[216:219], v[64:67], v[104:107], 0
	v_add_f32_e32 v240, v240, v131
	v_add_f32_e32 v241, v241, v155
	v_mov_b32_e32 v242, v240
	v_mov_b32_e32 v243, v241
	s_nop 1
	v_permlane16_swap_b32_e32 v240, v242
	v_permlane16_swap_b32_e32 v241, v243
	v_max_f32_e32 v240, v240, v242
	v_max_f32_e32 v241, v241, v243
	v_mov_b32_e32 v242, v240
	v_mov_b32_e32 v243, v241
	s_nop 1
	v_permlane32_swap_b32_e32 v240, v242
	v_permlane32_swap_b32_e32 v241, v243
	v_max3_f32 v240, v186, v240, v242
	v_sub_f32_e32 v244, v186, v240
	v_sub_f32_e32 v246, v240, v131
	v_exp_f32_e32 v244, v244
	v_mov_b32_e32 v186, v240
	v_max3_f32 v241, v185, v241, v243
	v_sub_f32_e32 v245, v185, v241
	v_sub_f32_e32 v247, v241, v155
	v_exp_f32_e32 v245, v245
	v_mov_b32_e32 v185, v241
	v_mfma_f32_16x16x32_bf16 v[220:223], v[68:71], v[104:107], 0
	v_sub_f32_e32 v112, v112, v246
	v_sub_f32_e32 v113, v113, v246
	v_sub_f32_e32 v114, v114, v246
	v_sub_f32_e32 v115, v115, v246
	v_sub_f32_e32 v116, v116, v246
	v_sub_f32_e32 v117, v117, v246
	v_sub_f32_e32 v118, v118, v246
	v_sub_f32_e32 v119, v119, v246
	v_sub_f32_e32 v120, v120, v247
	v_sub_f32_e32 v121, v121, v247
	v_sub_f32_e32 v122, v122, v247
	v_mfma_f32_16x16x32_bf16 v[208:211], v[72:75], v[100:103], v[208:211]
	v_sub_f32_e32 v123, v123, v247
	v_sub_f32_e32 v124, v124, v247
	v_sub_f32_e32 v125, v125, v247
	v_sub_f32_e32 v126, v126, v247
	v_sub_f32_e32 v127, v127, v247
	v_exp_f32_e32 v112, v112
	v_exp_f32_e32 v113, v113
	v_exp_f32_e32 v114, v114
	v_exp_f32_e32 v115, v115
	v_exp_f32_e32 v116, v116
	v_exp_f32_e32 v117, v117
	v_exp_f32_e32 v118, v118
	v_mfma_f32_16x16x32_bf16 v[212:215], v[76:79], v[100:103], v[212:215]
	v_exp_f32_e32 v119, v119
	v_exp_f32_e32 v120, v120
	v_exp_f32_e32 v121, v121
	v_exp_f32_e32 v122, v122
	v_exp_f32_e32 v123, v123
	v_exp_f32_e32 v124, v124
	v_exp_f32_e32 v125, v125
	v_exp_f32_e32 v126, v126
	v_exp_f32_e32 v127, v127
	v_add_f32_e32 v240, v112, v113
	v_add_f32_e32 v242, v114, v115
	v_add_f32_e32 v240, v240, v242
	v_mfma_f32_16x16x32_bf16 v[216:219], v[72:75], v[108:111], v[216:219]
	v_add_f32_e32 v242, v116, v117
	v_add_f32_e32 v240, v240, v242
	v_add_f32_e32 v242, v118, v119
	v_add_f32_e32 v240, v240, v242
	v_fma_f32 v157, v157, v244, v240
	v_add_f32_e32 v241, v120, v121
	v_add_f32_e32 v243, v122, v123
	v_add_f32_e32 v241, v241, v243
	v_add_f32_e32 v243, v124, v125
	v_add_f32_e32 v241, v241, v243
	v_add_f32_e32 v243, v126, v127
	v_add_f32_e32 v241, v241, v243
	v_mfma_f32_16x16x32_bf16 v[220:223], v[76:79], v[108:111], v[220:223]
	ds_read_b128 v[64:67], v248 offset:4096
	ds_read_b128 v[68:71], v248 offset:6144
	ds_read_b128 v[72:75], v249 offset:4096
	ds_read_b128 v[76:79], v249 offset:6144
	ds_read_b128 v[96:99], v191 offset:32768
	ds_read_b128 v[100:103], v192 offset:32768
	ds_read_b128 v[104:107], v191 offset:34816
	ds_read_b128 v[108:111], v192 offset:34816
	v_fma_f32 v156, v156, v245, v241
	v_cvt_pk_bf16_f32 v112, v112, v113
	v_cvt_pk_bf16_f32 v113, v114, v115
	v_cvt_pk_bf16_f32 v114, v116, v117
	v_cvt_pk_bf16_f32 v115, v118, v119
	v_cvt_pk_bf16_f32 v120, v120, v121
	v_cvt_pk_bf16_f32 v121, v122, v123
	v_cvt_pk_bf16_f32 v122, v124, v125
	v_cvt_pk_bf16_f32 v123, v126, v127
	v_cmp_neq_f32_e32 vcc, 1.0, v244
	s_nop 1
	s_cbranch_vccz .Lfoxf_r0
	v_mul_f32_e32 v60, v60, v244
	v_mul_f32_e32 v61, v61, v244
	v_mul_f32_e32 v62, v62, v244
	v_mul_f32_e32 v63, v63, v244
	v_mul_f32_e32 v56, v56, v244
	v_mul_f32_e32 v57, v57, v244
	v_mul_f32_e32 v58, v58, v244
	v_mul_f32_e32 v59, v59, v244
	v_mul_f32_e32 v52, v52, v244
	v_mul_f32_e32 v53, v53, v244
	v_mul_f32_e32 v54, v54, v244
	v_mul_f32_e32 v55, v55, v244
	v_mul_f32_e32 v48, v48, v244
	v_mul_f32_e32 v49, v49, v244
	v_mul_f32_e32 v50, v50, v244
	v_mul_f32_e32 v51, v51, v244

.Lfoxf_x1:
	v_sub_f32_e32 v208, v208, v224
	v_sub_f32_e32 v209, v209, v225
	v_sub_f32_e32 v210, v210, v226
	v_sub_f32_e32 v211, v211, v227
	v_sub_f32_e32 v212, v212, v228
	v_sub_f32_e32 v213, v213, v229
	v_mfma_f32_16x16x32_bf16 v[44:47], v[80:83], v[120:123], v[44:47]
	v_sub_f32_e32 v214, v214, v230
	v_sub_f32_e32 v215, v215, v231
	v_sub_f32_e32 v216, v216, v224
	v_sub_f32_e32 v217, v217, v225
	v_sub_f32_e32 v218, v218, v226
	v_sub_f32_e32 v219, v219, v227
	v_mfma_f32_16x16x32_bf16 v[56:59], v[84:87], v[112:115], v[56:59]
	v_sub_f32_e32 v220, v220, v228
	v_sub_f32_e32 v221, v221, v229
	v_sub_f32_e32 v222, v222, v230
	v_sub_f32_e32 v223, v223, v231
	v_max3_f32 v240, v208, v209, v210
	v_max3_f32 v240, v240, v211, v212
	v_mfma_f32_16x16x32_bf16 v[36:39], v[84:87], v[120:123], v[36:39]
	v_max3_f32 v240, v240, v213, v214
	v_max_f32_e32 v240, v240, v215
	v_max3_f32 v241, v216, v217, v218
	v_max3_f32 v241, v241, v219, v220
	v_max3_f32 v241, v241, v221, v222
	v_max_f32_e32 v241, v241, v223
	v_mfma_f32_16x16x32_bf16 v[52:55], v[88:91], v[112:115], v[52:55]
	v_add_f32_e32 v240, v240, v168
	v_add_f32_e32 v241, v241, v169
	v_mov_b32_e32 v242, v240
	v_mov_b32_e32 v243, v241
	s_nop 1
	v_permlane16_swap_b32_e32 v240, v242
	v_permlane16_swap_b32_e32 v241, v243
	v_max_f32_e32 v240, v240, v242
	v_max_f32_e32 v241, v241, v243
	v_mov_b32_e32 v242, v240
	v_mov_b32_e32 v243, v241
	s_nop 1
	v_permlane32_swap_b32_e32 v240, v242
	v_permlane32_swap_b32_e32 v241, v243
	v_max3_f32 v240, v167, v240, v242
	v_sub_f32_e32 v244, v167, v240
	v_sub_f32_e32 v246, v240, v168
	v_exp_f32_e32 v244, v244
	v_mfma_f32_16x16x32_bf16 v[32:35], v[88:91], v[120:123], v[32:35]
	v_mov_b32_e32 v167, v240
	v_max3_f32 v241, v166, v241, v243
	v_sub_f32_e32 v245, v166, v241
	v_sub_f32_e32 v247, v241, v169
	v_exp_f32_e32 v245, v245
	v_mov_b32_e32 v166, v241
	v_mfma_f32_16x16x32_bf16 v[48:51], v[92:95], v[112:115], v[48:51]
	v_sub_f32_e32 v208, v208, v246
	v_sub_f32_e32 v209, v209, v246
	v_sub_f32_e32 v210, v210, v246
	v_sub_f32_e32 v211, v211, v246
	v_sub_f32_e32 v212, v212, v246
	v_sub_f32_e32 v213, v213, v246
	v_mfma_f32_16x16x32_bf16 v[28:31], v[92:95], v[120:123], v[28:31]
	v_sub_f32_e32 v214, v214, v246
	v_sub_f32_e32 v215, v215, v246
	v_sub_f32_e32 v216, v216, v247
	v_sub_f32_e32 v217, v217, v247
	v_sub_f32_e32 v218, v218, v247
	s_waitcnt lgkmcnt(0)
	v_mfma_f32_16x16x32_bf16 v[112:115], v[64:67], v[96:99], 0
	v_sub_f32_e32 v219, v219, v247
	v_sub_f32_e32 v220, v220, v247
	v_sub_f32_e32 v221, v221, v247
	v_sub_f32_e32 v222, v222, v247
	v_sub_f32_e32 v223, v223, v247
	v_exp_f32_e32 v208, v208
	v_mfma_f32_16x16x32_bf16 v[116:119], v[68:71], v[96:99], 0
	v_exp_f32_e32 v209, v209
	v_exp_f32_e32 v210, v210
	v_exp_f32_e32 v211, v211
	v_exp_f32_e32 v212, v212
	v_exp_f32_e32 v213, v213
	v_exp_f32_e32 v214, v214
	v_mfma_f32_16x16x32_bf16 v[120:123], v[64:67], v[104:107], 0
	v_exp_f32_e32 v215, v215
	v_exp_f32_e32 v216, v216
	v_exp_f32_e32 v217, v217
	v_exp_f32_e32 v218, v218
	v_exp_f32_e32 v219, v219
	v_exp_f32_e32 v220, v220
	v_mfma_f32_16x16x32_bf16 v[124:127], v[68:71], v[104:107], 0
	v_exp_f32_e32 v221, v221
	v_exp_f32_e32 v222, v222
	v_exp_f32_e32 v223, v223
	v_add_f32_e32 v240, v208, v209
	v_add_f32_e32 v242, v210, v211
	v_add_f32_e32 v240, v240, v242
	v_mfma_f32_16x16x32_bf16 v[112:115], v[72:75], v[100:103], v[112:115]
	v_add_f32_e32 v242, v212, v213
	v_add_f32_e32 v240, v240, v242
	v_add_f32_e32 v242, v214, v215
	v_add_f32_e32 v240, v240, v242
	v_fma_f32 v151, v151, v244, v240
	v_add_f32_e32 v241, v216, v217
	v_mfma_f32_16x16x32_bf16 v[116:119], v[76:79], v[100:103], v[116:119]
	v_add_f32_e32 v243, v218, v219
	v_add_f32_e32 v241, v241, v243
	v_add_f32_e32 v243, v220, v221
	v_add_f32_e32 v241, v241, v243
	v_add_f32_e32 v243, v222, v223
	v_add_f32_e32 v241, v241, v243
	v_mfma_f32_16x16x32_bf16 v[120:123], v[72:75], v[108:111], v[120:123]
	v_fma_f32 v150, v150, v245, v241
	v_cvt_pk_bf16_f32 v208, v208, v209
	v_cvt_pk_bf16_f32 v209, v210, v211
	v_cvt_pk_bf16_f32 v210, v212, v213
	v_cvt_pk_bf16_f32 v211, v214, v215
	v_cvt_pk_bf16_f32 v216, v216, v217
	v_mfma_f32_16x16x32_bf16 v[124:127], v[76:79], v[108:111], v[124:127]
	ds_read_b128 v[96:99], v191 offset:36864
	ds_read_b128 v[100:103], v192 offset:36864
	ds_read_b128 v[104:107], v191 offset:38912
	ds_read_b128 v[108:111], v192 offset:38912
	v_cvt_pk_bf16_f32 v217, v218, v219
	v_cvt_pk_bf16_f32 v218, v220, v221
	v_cvt_pk_bf16_f32 v219, v222, v223
	v_cmp_neq_f32_e32 vcc, 1.0, v244
	s_nop 1
	s_cbranch_vccz .Lfoxf_r2
	v_mul_f32_e32 v40, v40, v244
	v_mul_f32_e32 v41, v41, v244
	v_mul_f32_e32 v42, v42, v244
	v_mul_f32_e32 v43, v43, v244
	v_mul_f32_e32 v24, v24, v244
	v_mul_f32_e32 v25, v25, v244
	v_mul_f32_e32 v26, v26, v244
	v_mul_f32_e32 v27, v27, v244
	v_mul_f32_e32 v20, v20, v244
	v_mul_f32_e32 v21, v21, v244
	v_mul_f32_e32 v22, v22, v244
	v_mul_f32_e32 v23, v23, v244
	v_mul_f32_e32 v16, v16, v244
	v_mul_f32_e32 v17, v17, v244
	v_mul_f32_e32 v18, v18, v244
	v_mul_f32_e32 v19, v19, v244

.Lfoxf_x2:
	v_sub_f32_e32 v112, v112, v232
	v_sub_f32_e32 v113, v113, v233
	v_sub_f32_e32 v114, v114, v234
	v_sub_f32_e32 v115, v115, v235
	v_sub_f32_e32 v116, v116, v236
	v_sub_f32_e32 v117, v117, v237
	v_mfma_f32_16x16x32_bf16 v[12:15], v[80:83], v[216:219], v[12:15]
	v_sub_f32_e32 v118, v118, v238
	v_sub_f32_e32 v119, v119, v239
	v_sub_f32_e32 v120, v120, v232
	v_sub_f32_e32 v121, v121, v233
	v_sub_f32_e32 v122, v122, v234
	v_sub_f32_e32 v123, v123, v235
	v_mfma_f32_16x16x32_bf16 v[24:27], v[84:87], v[208:211], v[24:27]
	v_sub_f32_e32 v124, v124, v236
	v_sub_f32_e32 v125, v125, v237
	v_sub_f32_e32 v126, v126, v238
	v_sub_f32_e32 v127, v127, v239
	v_max3_f32 v240, v112, v113, v114
	v_max3_f32 v240, v240, v115, v116
	v_mfma_f32_16x16x32_bf16 v[8:11], v[84:87], v[216:219], v[8:11]
	v_max3_f32 v240, v240, v117, v118
	v_max_f32_e32 v240, v240, v119
	v_max3_f32 v241, v120, v121, v122
	v_max3_f32 v241, v241, v123, v124
	v_max3_f32 v241, v241, v125, v126
	v_max_f32_e32 v241, v241, v127
	v_mfma_f32_16x16x32_bf16 v[20:23], v[88:91], v[208:211], v[20:23]
	v_add_f32_e32 v240, v240, v131
	v_add_f32_e32 v241, v241, v155
	v_mov_b32_e32 v242, v240
	v_mov_b32_e32 v243, v241
	s_nop 1
	v_permlane16_swap_b32_e32 v240, v242
	v_permlane16_swap_b32_e32 v241, v243
	v_max_f32_e32 v240, v240, v242
	v_max_f32_e32 v241, v241, v243
	v_mov_b32_e32 v242, v240
	v_mov_b32_e32 v243, v241
	s_nop 1
	v_permlane32_swap_b32_e32 v240, v242
	v_permlane32_swap_b32_e32 v241, v243
	v_max3_f32 v240, v186, v240, v242
	v_sub_f32_e32 v244, v186, v240
	v_sub_f32_e32 v246, v240, v131
	v_exp_f32_e32 v244, v244
	v_mfma_f32_16x16x32_bf16 v[0:3], v[88:91], v[216:219], v[0:3]
	v_mov_b32_e32 v186, v240
	v_max3_f32 v241, v185, v241, v243
	v_sub_f32_e32 v245, v185, v241
	v_sub_f32_e32 v247, v241, v155
	v_exp_f32_e32 v245, v245
	v_mov_b32_e32 v185, v241
	v_mfma_f32_16x16x32_bf16 v[16:19], v[92:95], v[208:211], v[16:19]
	v_sub_f32_e32 v112, v112, v246
	v_sub_f32_e32 v113, v113, v246
	v_sub_f32_e32 v114, v114, v246
	v_sub_f32_e32 v115, v115, v246
	v_sub_f32_e32 v116, v116, v246
	v_sub_f32_e32 v117, v117, v246
	v_mfma_f32_16x16x32_bf16 v[4:7], v[92:95], v[216:219], v[4:7]
	v_sub_f32_e32 v118, v118, v246
	v_sub_f32_e32 v119, v119, v246
	v_sub_f32_e32 v120, v120, v247
	v_sub_f32_e32 v121, v121, v247
	v_sub_f32_e32 v122, v122, v247
	ds_read_b64 v[80:81], v189 offset:8192
	ds_read_b64 v[82:83], v190 offset:8192
	ds_read_b64 v[84:85], v189 offset:10240
	ds_read_b64 v[86:87], v190 offset:10240
	ds_read_b64 v[88:89], v189 offset:12288
	ds_read_b64 v[90:91], v190 offset:12288
	ds_read_b64 v[92:93], v189 offset:14336
	ds_read_b64 v[94:95], v190 offset:14336
	s_waitcnt lgkmcnt(8)
	v_mfma_f32_16x16x32_bf16 v[208:211], v[64:67], v[96:99], 0
	v_sub_f32_e32 v123, v123, v247
	v_sub_f32_e32 v124, v124, v247
	v_sub_f32_e32 v125, v125, v247
	v_sub_f32_e32 v126, v126, v247
	v_sub_f32_e32 v127, v127, v247
	v_exp_f32_e32 v112, v112
	v_mfma_f32_16x16x32_bf16 v[212:215], v[68:71], v[96:99], 0
	v_exp_f32_e32 v113, v113
	v_exp_f32_e32 v114, v114
	v_exp_f32_e32 v115, v115
	v_exp_f32_e32 v116, v116
	v_exp_f32_e32 v117, v117
	v_exp_f32_e32 v118, v118
	v_mfma_f32_16x16x32_bf16 v[216:219], v[64:67], v[104:107], 0
	v_exp_f32_e32 v119, v119
	v_exp_f32_e32 v120, v120
	v_exp_f32_e32 v121, v121
	v_exp_f32_e32 v122, v122
	v_exp_f32_e32 v123, v123
	v_exp_f32_e32 v124, v124
	v_mfma_f32_16x16x32_bf16 v[220:223], v[68:71], v[104:107], 0
	v_exp_f32_e32 v125, v125
	v_exp_f32_e32 v126, v126
	v_exp_f32_e32 v127, v127
	v_add_f32_e32 v240, v112, v113
	v_add_f32_e32 v242, v114, v115
	v_add_f32_e32 v240, v240, v242
	v_mfma_f32_16x16x32_bf16 v[208:211], v[72:75], v[100:103], v[208:211]
	v_add_f32_e32 v242, v116, v117
	v_add_f32_e32 v240, v240, v242
	v_add_f32_e32 v242, v118, v119
	v_add_f32_e32 v240, v240, v242
	v_fma_f32 v157, v157, v244, v240
	v_add_f32_e32 v241, v120, v121
	v_mfma_f32_16x16x32_bf16 v[212:215], v[76:79], v[100:103], v[212:215]
	v_add_f32_e32 v243, v122, v123
	v_add_f32_e32 v241, v241, v243
	v_add_f32_e32 v243, v124, v125
	v_add_f32_e32 v241, v241, v243
	v_add_f32_e32 v243, v126, v127
	v_add_f32_e32 v241, v241, v243
	v_mfma_f32_16x16x32_bf16 v[216:219], v[72:75], v[108:111], v[216:219]
	v_fma_f32 v156, v156, v245, v241
	v_cvt_pk_bf16_f32 v112, v112, v113
	v_cvt_pk_bf16_f32 v113, v114, v115
	v_cvt_pk_bf16_f32 v114, v116, v117
	v_cvt_pk_bf16_f32 v115, v118, v119
	v_cvt_pk_bf16_f32 v120, v120, v121
	v_mfma_f32_16x16x32_bf16 v[220:223], v[76:79], v[108:111], v[220:223]
	v_cvt_pk_bf16_f32 v121, v122, v123
	v_cvt_pk_bf16_f32 v122, v124, v125
	v_cvt_pk_bf16_f32 v123, v126, v127
	v_cmp_neq_f32_e32 vcc, 1.0, v244
	s_nop 1
	s_cbranch_vccz .Lfoxf_r4
	v_mul_f32_e32 v60, v60, v244
	v_mul_f32_e32 v61, v61, v244
	v_mul_f32_e32 v62, v62, v244
	v_mul_f32_e32 v63, v63, v244
	v_mul_f32_e32 v56, v56, v244
	v_mul_f32_e32 v57, v57, v244
	v_mul_f32_e32 v58, v58, v244
	v_mul_f32_e32 v59, v59, v244
	v_mul_f32_e32 v52, v52, v244
	v_mul_f32_e32 v53, v53, v244
	v_mul_f32_e32 v54, v54, v244
	v_mul_f32_e32 v55, v55, v244
	v_mul_f32_e32 v48, v48, v244
	v_mul_f32_e32 v49, v49, v244
	v_mul_f32_e32 v50, v50, v244
	v_mul_f32_e32 v51, v51, v244

.Lfoxf_x3:
	v_sub_f32_e32 v208, v208, v232
	v_sub_f32_e32 v209, v209, v233
	v_sub_f32_e32 v210, v210, v234
	v_sub_f32_e32 v211, v211, v235
	v_sub_f32_e32 v212, v212, v236
	v_sub_f32_e32 v213, v213, v237
	v_sub_f32_e32 v214, v214, v238
	v_sub_f32_e32 v215, v215, v239
	v_sub_f32_e32 v216, v216, v232
	v_sub_f32_e32 v217, v217, v233
	v_sub_f32_e32 v218, v218, v234
	v_sub_f32_e32 v219, v219, v235
	v_mfma_f32_16x16x32_bf16 v[44:47], v[80:83], v[120:123], v[44:47]
	v_sub_f32_e32 v220, v220, v236
	v_sub_f32_e32 v221, v221, v237
	v_sub_f32_e32 v222, v222, v238
	v_sub_f32_e32 v223, v223, v239
	v_max3_f32 v240, v208, v209, v210
	v_max3_f32 v240, v240, v211, v212
	v_max3_f32 v240, v240, v213, v214
	v_max_f32_e32 v240, v240, v215
	v_max3_f32 v241, v216, v217, v218
	v_max3_f32 v241, v241, v219, v220
	v_max3_f32 v241, v241, v221, v222
	v_max_f32_e32 v241, v241, v223
	v_mfma_f32_16x16x32_bf16 v[56:59], v[84:87], v[112:115], v[56:59]
	v_add_f32_e32 v240, v240, v168
	v_add_f32_e32 v241, v241, v169
	v_mov_b32_e32 v242, v240
	v_mov_b32_e32 v243, v241
	s_nop 1
	v_permlane16_swap_b32_e32 v240, v242
	v_permlane16_swap_b32_e32 v241, v243
	v_max_f32_e32 v240, v240, v242
	v_max_f32_e32 v241, v241, v243
	v_mov_b32_e32 v242, v240
	v_mov_b32_e32 v243, v241
	s_nop 1
	v_permlane32_swap_b32_e32 v240, v242
	v_permlane32_swap_b32_e32 v241, v243
	v_max3_f32 v240, v167, v240, v242
	v_sub_f32_e32 v244, v167, v240
	v_sub_f32_e32 v246, v240, v168
	v_exp_f32_e32 v244, v244
	v_mov_b32_e32 v167, v240
	v_max3_f32 v241, v166, v241, v243
	v_sub_f32_e32 v245, v166, v241
	v_sub_f32_e32 v247, v241, v169
	v_exp_f32_e32 v245, v245
	v_mov_b32_e32 v166, v241
	v_mfma_f32_16x16x32_bf16 v[36:39], v[84:87], v[120:123], v[36:39]
	v_sub_f32_e32 v208, v208, v246
	v_sub_f32_e32 v209, v209, v246
	v_sub_f32_e32 v210, v210, v246
	v_sub_f32_e32 v211, v211, v246
	v_sub_f32_e32 v212, v212, v246
	v_sub_f32_e32 v213, v213, v246
	v_sub_f32_e32 v214, v214, v246
	v_sub_f32_e32 v215, v215, v246
	v_sub_f32_e32 v216, v216, v247
	v_sub_f32_e32 v217, v217, v247
	v_sub_f32_e32 v218, v218, v247
	v_mfma_f32_16x16x32_bf16 v[52:55], v[88:91], v[112:115], v[52:55]
	v_sub_f32_e32 v219, v219, v247
	v_sub_f32_e32 v220, v220, v247
	v_sub_f32_e32 v221, v221, v247
	v_sub_f32_e32 v222, v222, v247
	v_sub_f32_e32 v223, v223, v247
	v_exp_f32_e32 v208, v208
	v_exp_f32_e32 v209, v209
	v_exp_f32_e32 v210, v210
	v_exp_f32_e32 v211, v211
	v_exp_f32_e32 v212, v212
	v_exp_f32_e32 v213, v213
	v_exp_f32_e32 v214, v214
	v_mfma_f32_16x16x32_bf16 v[32:35], v[88:91], v[120:123], v[32:35]
	v_exp_f32_e32 v215, v215
	v_exp_f32_e32 v216, v216
	v_exp_f32_e32 v217, v217
	v_exp_f32_e32 v218, v218
	v_exp_f32_e32 v219, v219
	v_exp_f32_e32 v220, v220
	v_exp_f32_e32 v221, v221
	v_exp_f32_e32 v222, v222
	v_exp_f32_e32 v223, v223
	v_add_f32_e32 v240, v208, v209
	v_add_f32_e32 v242, v210, v211
	v_add_f32_e32 v240, v240, v242
	v_mfma_f32_16x16x32_bf16 v[48:51], v[92:95], v[112:115], v[48:51]
	v_add_f32_e32 v242, v212, v213
	v_add_f32_e32 v240, v240, v242
	v_add_f32_e32 v242, v214, v215
	v_add_f32_e32 v240, v240, v242
	v_fma_f32 v151, v151, v244, v240
	v_add_f32_e32 v241, v216, v217
	v_add_f32_e32 v243, v218, v219
	v_add_f32_e32 v241, v241, v243
	v_add_f32_e32 v243, v220, v221
	v_add_f32_e32 v241, v241, v243
	v_add_f32_e32 v243, v222, v223
	v_add_f32_e32 v241, v241, v243
	v_mfma_f32_16x16x32_bf16 v[28:31], v[92:95], v[120:123], v[28:31]
	v_fma_f32 v150, v150, v245, v241
	v_cvt_pk_bf16_f32 v208, v208, v209
	v_cvt_pk_bf16_f32 v209, v210, v211
	v_cvt_pk_bf16_f32 v210, v212, v213
	v_cvt_pk_bf16_f32 v211, v214, v215
	v_cvt_pk_bf16_f32 v216, v216, v217
	v_cvt_pk_bf16_f32 v217, v218, v219
	v_cvt_pk_bf16_f32 v218, v220, v221
	v_cvt_pk_bf16_f32 v219, v222, v223
	v_cmp_neq_f32_e32 vcc, 1.0, v244
	s_nop 1
	s_cbranch_vccz .Lfoxf_r6
	v_mul_f32_e32 v40, v40, v244
	v_mul_f32_e32 v41, v41, v244
	v_mul_f32_e32 v42, v42, v244
	v_mul_f32_e32 v43, v43, v244
	v_mul_f32_e32 v24, v24, v244
	v_mul_f32_e32 v25, v25, v244
	v_mul_f32_e32 v26, v26, v244
	v_mul_f32_e32 v27, v27, v244
	v_mul_f32_e32 v20, v20, v244
	v_mul_f32_e32 v21, v21, v244
	v_mul_f32_e32 v22, v22, v244
	v_mul_f32_e32 v23, v23, v244
	v_mul_f32_e32 v16, v16, v244
	v_mul_f32_e32 v17, v17, v244
	v_mul_f32_e32 v18, v18, v244
	v_mul_f32_e32 v19, v19, v244

.Lfoxf_lazy:
	v_min3_f32 v240, v186, v185, v167
	v_min_f32_e32 v240, v240, v166
	v_cmp_gt_f32_e32 vcc, 0xefa18f08, v240
	s_nop 1
	s_cbranch_vccnz .Lfoxf_fast
	s_lshl_b32 s84, s23, 6
	v_lshl_add_u64 v[158:159], s[84:85], 2, v[146:147]
	global_load_dwordx4 v[224:227], v[158:159], off
	global_load_dwordx4 v[228:231], v[158:159], off offset:64
	global_load_dwordx4 v[232:235], v[158:159], off offset:128
	global_load_dwordx4 v[236:239], v[158:159], off offset:192
	s_lshl_b32 s4, s21, 14
	v_or_b32_e32 v193, s4, v178
	v_add_u32_e32 v248, v193, v176
	v_add_u32_e32 v249, v193, v177
	v_add_u32_e32 v191, v175, v176
	v_add_u32_e32 v192, v175, v177
	v_add_u32_e32 v187, v193, v181
	v_add_u32_e32 v188, v193, v182
	v_add_u32_e32 v189, v193, v183
	v_add_u32_e32 v190, v193, v184
	ds_read_b128 v[64:67], v248
	ds_read_b128 v[68:71], v248 offset:2048
	ds_read_b128 v[72:75], v249
	ds_read_b128 v[76:79], v249 offset:2048
	ds_read_b128 v[96:99], v191 offset:32768
	ds_read_b128 v[100:103], v192 offset:32768
	ds_read_b128 v[104:107], v191 offset:34816
	ds_read_b128 v[108:111], v192 offset:34816
	ds_read_b64 v[80:81], v187 offset:8192
	ds_read_b64 v[82:83], v188 offset:8192
	ds_read_b64 v[84:85], v187 offset:10240
	ds_read_b64 v[86:87], v188 offset:10240
	ds_read_b64 v[88:89], v187 offset:12288
	ds_read_b64 v[90:91], v188 offset:12288
	ds_read_b64 v[92:93], v187 offset:14336
	ds_read_b64 v[94:95], v188 offset:14336
	v_sub_f32_e32 v244, v131, v186
	v_sub_f32_e32 v245, v155, v185
	v_sub_f32_e32 v246, v168, v167
	v_sub_f32_e32 v247, v169, v166
	s_waitcnt vmcnt(2)
	s_waitcnt lgkmcnt(8)
	v_sub_f32_e32 v112, v244, v224
	v_sub_f32_e32 v113, v244, v225
	v_sub_f32_e32 v114, v244, v226
	v_sub_f32_e32 v115, v244, v227
	v_sub_f32_e32 v116, v244, v228
	v_sub_f32_e32 v117, v244, v229
	v_sub_f32_e32 v118, v244, v230
	v_sub_f32_e32 v119, v244, v231
	v_mfma_f32_16x16x32_bf16 v[112:115], v[64:67], v[96:99], v[112:115]
	v_sub_f32_e32 v120, v245, v224
	v_sub_f32_e32 v121, v245, v225
	v_sub_f32_e32 v122, v245, v226
	v_sub_f32_e32 v123, v245, v227
	v_mfma_f32_16x16x32_bf16 v[116:119], v[68:71], v[96:99], v[116:119]
	v_sub_f32_e32 v124, v245, v228
	v_sub_f32_e32 v125, v245, v229
	v_sub_f32_e32 v126, v245, v230
	v_sub_f32_e32 v127, v245, v231
	v_mfma_f32_16x16x32_bf16 v[120:123], v[64:67], v[104:107], v[120:123]
	v_mfma_f32_16x16x32_bf16 v[112:115], v[72:75], v[100:103], v[112:115]
	v_mfma_f32_16x16x32_bf16 v[124:127], v[68:71], v[104:107], v[124:127]
	v_mfma_f32_16x16x32_bf16 v[116:119], v[76:79], v[100:103], v[116:119]
	v_mfma_f32_16x16x32_bf16 v[120:123], v[72:75], v[108:111], v[120:123]
	v_mfma_f32_16x16x32_bf16 v[124:127], v[76:79], v[108:111], v[124:127]
	ds_read_b128 v[96:99], v191 offset:36864
	ds_read_b128 v[100:103], v192 offset:36864
	ds_read_b128 v[104:107], v191 offset:38912
	ds_read_b128 v[108:111], v192 offset:38912
	s_nop 0
	v_max3_f32 v240, v112, v113, v114
	v_max3_f32 v240, v240, v115, v116
	v_max3_f32 v240, v240, v117, v118
	v_max_f32_e32 v240, v240, v119
	v_max3_f32 v241, v120, v121, v122
	v_max3_f32 v241, v241, v123, v124
	v_max3_f32 v241, v241, v125, v126
	v_max_f32_e32 v241, v241, v127
	v_max_f32_e32 v240, v240, v241
	v_cmp_lt_f32_e32 vcc, 0x41000000, v240
	s_nop 1
	s_cbranch_vccnz .Lfoxf_fb0
	s_waitcnt lgkmcnt(0)
	v_sub_f32_e32 v208, v246, v224
	v_sub_f32_e32 v209, v246, v225
	v_sub_f32_e32 v210, v246, v226
	v_sub_f32_e32 v211, v246, v227
	v_sub_f32_e32 v212, v246, v228
	v_sub_f32_e32 v213, v246, v229
	v_sub_f32_e32 v214, v246, v230
	v_sub_f32_e32 v215, v246, v231
	v_mfma_f32_16x16x32_bf16 v[208:211], v[64:67], v[96:99], v[208:211]
	v_exp_f32_e32 v112, v112
	v_exp_f32_e32 v113, v113
	v_exp_f32_e32 v114, v114
	v_exp_f32_e32 v115, v115
	v_exp_f32_e32 v116, v116
	v_sub_f32_e32 v216, v247, v224
	v_sub_f32_e32 v217, v247, v225
	v_sub_f32_e32 v218, v247, v226
	v_sub_f32_e32 v219, v247, v227
	v_mfma_f32_16x16x32_bf16 v[212:215], v[68:71], v[96:99], v[212:215]
	v_exp_f32_e32 v117, v117
	v_exp_f32_e32 v118, v118
	v_exp_f32_e32 v119, v119
	v_exp_f32_e32 v120, v120
	v_exp_f32_e32 v121, v121
	v_sub_f32_e32 v220, v247, v228
	v_sub_f32_e32 v221, v247, v229
	v_sub_f32_e32 v222, v247, v230
	v_sub_f32_e32 v223, v247, v231
	v_mfma_f32_16x16x32_bf16 v[216:219], v[64:67], v[104:107], v[216:219]
	v_exp_f32_e32 v122, v122
	v_exp_f32_e32 v123, v123
	v_exp_f32_e32 v124, v124
	v_exp_f32_e32 v125, v125
	v_exp_f32_e32 v126, v126
	v_mfma_f32_16x16x32_bf16 v[208:211], v[72:75], v[100:103], v[208:211]
	v_exp_f32_e32 v127, v127
	v_add_f32_e32 v240, v112, v113
	v_add_f32_e32 v242, v114, v115
	v_add_f32_e32 v240, v240, v242
	v_add_f32_e32 v242, v116, v117
	v_mfma_f32_16x16x32_bf16 v[220:223], v[68:71], v[104:107], v[220:223]
	v_add_f32_e32 v240, v240, v242
	v_add_f32_e32 v242, v118, v119
	v_add_f32_e32 v240, v240, v242
	v_add_f32_e32 v157, v157, v240
	v_add_f32_e32 v241, v120, v121
	v_mfma_f32_16x16x32_bf16 v[212:215], v[76:79], v[100:103], v[212:215]
	v_add_f32_e32 v243, v122, v123
	v_add_f32_e32 v241, v241, v243
	v_add_f32_e32 v243, v124, v125
	v_add_f32_e32 v241, v241, v243
	v_add_f32_e32 v243, v126, v127
	v_mfma_f32_16x16x32_bf16 v[216:219], v[72:75], v[108:111], v[216:219]
	v_add_f32_e32 v241, v241, v243
	v_add_f32_e32 v156, v156, v241
	v_cvt_pk_bf16_f32 v112, v112, v113
	v_cvt_pk_bf16_f32 v113, v114, v115
	v_cvt_pk_bf16_f32 v114, v116, v117
	v_mfma_f32_16x16x32_bf16 v[220:223], v[76:79], v[108:111], v[220:223]
	ds_read_b128 v[64:67], v248 offset:4096
	ds_read_b128 v[68:71], v248 offset:6144
	ds_read_b128 v[72:75], v249 offset:4096
	ds_read_b128 v[76:79], v249 offset:6144
	ds_read_b128 v[96:99], v191 offset:32768
	ds_read_b128 v[100:103], v192 offset:32768
	ds_read_b128 v[104:107], v191 offset:34816
	ds_read_b128 v[108:111], v192 offset:34816
	v_cvt_pk_bf16_f32 v115, v118, v119
	v_cvt_pk_bf16_f32 v120, v120, v121
	v_cvt_pk_bf16_f32 v121, v122, v123
	v_cvt_pk_bf16_f32 v122, v124, v125
	v_cvt_pk_bf16_f32 v123, v126, v127
	s_waitcnt lgkmcnt(12)
	v_mfma_f32_16x16x32_bf16 v[60:63], v[80:83], v[112:115], v[60:63]
	v_max3_f32 v240, v208, v209, v210
	v_max3_f32 v240, v240, v211, v212
	v_max3_f32 v240, v240, v213, v214
	v_max_f32_e32 v240, v240, v215
	v_max3_f32 v241, v216, v217, v218
	v_max3_f32 v241, v241, v219, v220
	v_max3_f32 v241, v241, v221, v222
	v_max_f32_e32 v241, v241, v223
	v_max_f32_e32 v240, v240, v241
	v_cmp_lt_f32_e32 vcc, 0x41000000, v240
	s_nop 1
	s_cbranch_vccnz .Lfoxf_fb1
	v_mfma_f32_16x16x32_bf16 v[44:47], v[80:83], v[120:123], v[44:47]
	v_exp_f32_e32 v208, v208
	v_exp_f32_e32 v209, v209
	v_exp_f32_e32 v210, v210
	v_mfma_f32_16x16x32_bf16 v[56:59], v[84:87], v[112:115], v[56:59]
	v_exp_f32_e32 v211, v211
	v_exp_f32_e32 v212, v212
	v_exp_f32_e32 v213, v213
	v_mfma_f32_16x16x32_bf16 v[36:39], v[84:87], v[120:123], v[36:39]
	v_exp_f32_e32 v214, v214
	v_exp_f32_e32 v215, v215
	v_mfma_f32_16x16x32_bf16 v[52:55], v[88:91], v[112:115], v[52:55]
	v_exp_f32_e32 v216, v216
	v_exp_f32_e32 v217, v217
	v_exp_f32_e32 v218, v218
	v_mfma_f32_16x16x32_bf16 v[32:35], v[88:91], v[120:123], v[32:35]
	v_exp_f32_e32 v219, v219
	v_exp_f32_e32 v220, v220
	v_exp_f32_e32 v221, v221
	v_mfma_f32_16x16x32_bf16 v[48:51], v[92:95], v[112:115], v[48:51]
	v_exp_f32_e32 v222, v222
	v_exp_f32_e32 v223, v223
	v_mfma_f32_16x16x32_bf16 v[28:31], v[92:95], v[120:123], v[28:31]
	v_add_f32_e32 v240, v208, v209
	v_add_f32_e32 v242, v210, v211
	v_add_f32_e32 v240, v240, v242
	s_waitcnt lgkmcnt(0)
	s_waitcnt vmcnt(0)
	v_sub_f32_e32 v112, v244, v232
	v_sub_f32_e32 v113, v244, v233
	v_sub_f32_e32 v114, v244, v234
	v_sub_f32_e32 v115, v244, v235
	v_sub_f32_e32 v116, v244, v236
	v_sub_f32_e32 v117, v244, v237
	v_sub_f32_e32 v118, v244, v238
	v_sub_f32_e32 v119, v244, v239
	v_mfma_f32_16x16x32_bf16 v[112:115], v[64:67], v[96:99], v[112:115]
	v_add_f32_e32 v242, v212, v213
	v_add_f32_e32 v240, v240, v242
	v_add_f32_e32 v242, v214, v215
	v_sub_f32_e32 v120, v245, v232
	v_sub_f32_e32 v121, v245, v233
	v_sub_f32_e32 v122, v245, v234
	v_sub_f32_e32 v123, v245, v235
	v_mfma_f32_16x16x32_bf16 v[116:119], v[68:71], v[96:99], v[116:119]
	v_add_f32_e32 v240, v240, v242
	v_add_f32_e32 v151, v151, v240
	v_sub_f32_e32 v124, v245, v236
	v_sub_f32_e32 v125, v245, v237
	v_sub_f32_e32 v126, v245, v238
	v_sub_f32_e32 v127, v245, v239
	v_mfma_f32_16x16x32_bf16 v[120:123], v[64:67], v[104:107], v[120:123]
	v_add_f32_e32 v241, v216, v217
	v_add_f32_e32 v243, v218, v219
	v_add_f32_e32 v241, v241, v243
	v_mfma_f32_16x16x32_bf16 v[112:115], v[72:75], v[100:103], v[112:115]
	v_add_f32_e32 v243, v220, v221
	v_add_f32_e32 v241, v241, v243
	v_add_f32_e32 v243, v222, v223
	v_mfma_f32_16x16x32_bf16 v[124:127], v[68:71], v[104:107], v[124:127]
	v_add_f32_e32 v241, v241, v243
	v_add_f32_e32 v150, v150, v241
	v_mfma_f32_16x16x32_bf16 v[116:119], v[76:79], v[100:103], v[116:119]
	v_cvt_pk_bf16_f32 v208, v208, v209
	v_cvt_pk_bf16_f32 v209, v210, v211
	v_cvt_pk_bf16_f32 v210, v212, v213
	v_mfma_f32_16x16x32_bf16 v[120:123], v[72:75], v[108:111], v[120:123]
	v_cvt_pk_bf16_f32 v211, v214, v215
	v_cvt_pk_bf16_f32 v216, v216, v217
	v_cvt_pk_bf16_f32 v217, v218, v219
	v_mfma_f32_16x16x32_bf16 v[124:127], v[76:79], v[108:111], v[124:127]
	ds_read_b128 v[96:99], v191 offset:36864
	ds_read_b128 v[100:103], v192 offset:36864
	ds_read_b128 v[104:107], v191 offset:38912
	ds_read_b128 v[108:111], v192 offset:38912
	v_cvt_pk_bf16_f32 v218, v220, v221
	v_cvt_pk_bf16_f32 v219, v222, v223
	v_mfma_f32_16x16x32_bf16 v[40:43], v[80:83], v[208:211], v[40:43]
	v_max3_f32 v240, v112, v113, v114
	v_max3_f32 v240, v240, v115, v116
	v_max3_f32 v240, v240, v117, v118
	v_max_f32_e32 v240, v240, v119
	v_max3_f32 v241, v120, v121, v122
	v_max3_f32 v241, v241, v123, v124
	v_max3_f32 v241, v241, v125, v126
	v_max_f32_e32 v241, v241, v127
	v_max_f32_e32 v240, v240, v241
	v_cmp_lt_f32_e32 vcc, 0x41000000, v240
	s_nop 1
	s_cbranch_vccnz .Lfoxf_fb2
	v_mfma_f32_16x16x32_bf16 v[12:15], v[80:83], v[216:219], v[12:15]
	v_exp_f32_e32 v112, v112
	v_exp_f32_e32 v113, v113
	v_exp_f32_e32 v114, v114
	v_mfma_f32_16x16x32_bf16 v[24:27], v[84:87], v[208:211], v[24:27]
	v_exp_f32_e32 v115, v115
	v_exp_f32_e32 v116, v116
	v_exp_f32_e32 v117, v117
	v_mfma_f32_16x16x32_bf16 v[8:11], v[84:87], v[216:219], v[8:11]
	v_exp_f32_e32 v118, v118
	v_exp_f32_e32 v119, v119
	v_mfma_f32_16x16x32_bf16 v[20:23], v[88:91], v[208:211], v[20:23]
	v_exp_f32_e32 v120, v120
	v_exp_f32_e32 v121, v121
	v_exp_f32_e32 v122, v122
	v_mfma_f32_16x16x32_bf16 v[0:3], v[88:91], v[216:219], v[0:3]
	v_exp_f32_e32 v123, v123
	v_exp_f32_e32 v124, v124
	v_exp_f32_e32 v125, v125
	v_mfma_f32_16x16x32_bf16 v[16:19], v[92:95], v[208:211], v[16:19]
	v_exp_f32_e32 v126, v126
	v_exp_f32_e32 v127, v127
	v_mfma_f32_16x16x32_bf16 v[4:7], v[92:95], v[216:219], v[4:7]
	v_add_f32_e32 v240, v112, v113
	v_add_f32_e32 v242, v114, v115
	v_add_f32_e32 v240, v240, v242
	ds_read_b64 v[80:81], v189 offset:8192
	ds_read_b64 v[82:83], v190 offset:8192
	ds_read_b64 v[84:85], v189 offset:10240
	ds_read_b64 v[86:87], v190 offset:10240
	ds_read_b64 v[88:89], v189 offset:12288
	ds_read_b64 v[90:91], v190 offset:12288
	ds_read_b64 v[92:93], v189 offset:14336
	ds_read_b64 v[94:95], v190 offset:14336
	s_waitcnt lgkmcnt(8)
	v_sub_f32_e32 v208, v246, v232
	v_sub_f32_e32 v209, v246, v233
	v_sub_f32_e32 v210, v246, v234
	v_sub_f32_e32 v211, v246, v235
	v_sub_f32_e32 v212, v246, v236
	v_sub_f32_e32 v213, v246, v237
	v_sub_f32_e32 v214, v246, v238
	v_sub_f32_e32 v215, v246, v239
	v_mfma_f32_16x16x32_bf16 v[208:211], v[64:67], v[96:99], v[208:211]
	v_add_f32_e32 v242, v116, v117
	v_add_f32_e32 v240, v240, v242
	v_add_f32_e32 v242, v118, v119
	v_sub_f32_e32 v216, v247, v232
	v_sub_f32_e32 v217, v247, v233
	v_sub_f32_e32 v218, v247, v234
	v_sub_f32_e32 v219, v247, v235
	v_mfma_f32_16x16x32_bf16 v[212:215], v[68:71], v[96:99], v[212:215]
	v_add_f32_e32 v240, v240, v242
	v_add_f32_e32 v157, v157, v240
	v_sub_f32_e32 v220, v247, v236
	v_sub_f32_e32 v221, v247, v237
	v_sub_f32_e32 v222, v247, v238
	v_sub_f32_e32 v223, v247, v239
	v_mfma_f32_16x16x32_bf16 v[216:219], v[64:67], v[104:107], v[216:219]
	v_add_f32_e32 v241, v120, v121
	v_add_f32_e32 v243, v122, v123
	v_add_f32_e32 v241, v241, v243
	v_mfma_f32_16x16x32_bf16 v[208:211], v[72:75], v[100:103], v[208:211]
	v_add_f32_e32 v243, v124, v125
	v_add_f32_e32 v241, v241, v243
	v_add_f32_e32 v243, v126, v127
	v_mfma_f32_16x16x32_bf16 v[220:223], v[68:71], v[104:107], v[220:223]
	v_add_f32_e32 v241, v241, v243
	v_add_f32_e32 v156, v156, v241
	v_mfma_f32_16x16x32_bf16 v[212:215], v[76:79], v[100:103], v[212:215]
	v_cvt_pk_bf16_f32 v112, v112, v113
	v_cvt_pk_bf16_f32 v113, v114, v115
	v_cvt_pk_bf16_f32 v114, v116, v117
	v_mfma_f32_16x16x32_bf16 v[216:219], v[72:75], v[108:111], v[216:219]
	v_cvt_pk_bf16_f32 v115, v118, v119
	v_cvt_pk_bf16_f32 v120, v120, v121
	v_cvt_pk_bf16_f32 v121, v122, v123
	v_mfma_f32_16x16x32_bf16 v[220:223], v[76:79], v[108:111], v[220:223]
	v_cvt_pk_bf16_f32 v122, v124, v125
	v_cvt_pk_bf16_f32 v123, v126, v127
	s_waitcnt lgkmcnt(0)
	v_mfma_f32_16x16x32_bf16 v[60:63], v[80:83], v[112:115], v[60:63]
	v_max3_f32 v240, v208, v209, v210
	v_max3_f32 v240, v240, v211, v212
	v_max3_f32 v240, v240, v213, v214
	v_max_f32_e32 v240, v240, v215
	v_max3_f32 v241, v216, v217, v218
	v_max3_f32 v241, v241, v219, v220
	v_max3_f32 v241, v241, v221, v222
	v_max_f32_e32 v241, v241, v223
	v_max_f32_e32 v240, v240, v241
	v_cmp_lt_f32_e32 vcc, 0x41000000, v240
	s_nop 1
	s_cbranch_vccnz .Lfoxf_fb3
	v_mfma_f32_16x16x32_bf16 v[44:47], v[80:83], v[120:123], v[44:47]
	v_exp_f32_e32 v208, v208
	v_exp_f32_e32 v209, v209
	v_exp_f32_e32 v210, v210
	v_exp_f32_e32 v211, v211
	v_exp_f32_e32 v212, v212
	v_exp_f32_e32 v213, v213
	v_mfma_f32_16x16x32_bf16 v[56:59], v[84:87], v[112:115], v[56:59]
	v_exp_f32_e32 v214, v214
	v_exp_f32_e32 v215, v215
	v_exp_f32_e32 v216, v216
	v_exp_f32_e32 v217, v217
	v_exp_f32_e32 v218, v218
	v_exp_f32_e32 v219, v219
	v_mfma_f32_16x16x32_bf16 v[36:39], v[84:87], v[120:123], v[36:39]
	v_exp_f32_e32 v220, v220
	v_exp_f32_e32 v221, v221
	v_exp_f32_e32 v222, v222
	v_exp_f32_e32 v223, v223
	v_add_f32_e32 v240, v208, v209
	v_add_f32_e32 v242, v210, v211
	v_mfma_f32_16x16x32_bf16 v[52:55], v[88:91], v[112:115], v[52:55]
	v_add_f32_e32 v240, v240, v242
	v_add_f32_e32 v242, v212, v213
	v_add_f32_e32 v240, v240, v242
	v_add_f32_e32 v242, v214, v215
	v_add_f32_e32 v240, v240, v242
	v_mfma_f32_16x16x32_bf16 v[32:35], v[88:91], v[120:123], v[32:35]
	v_add_f32_e32 v151, v151, v240
	v_add_f32_e32 v241, v216, v217
	v_add_f32_e32 v243, v218, v219
	v_add_f32_e32 v241, v241, v243
	v_add_f32_e32 v243, v220, v221
	v_add_f32_e32 v241, v241, v243
	v_mfma_f32_16x16x32_bf16 v[48:51], v[92:95], v[112:115], v[48:51]
	v_add_f32_e32 v243, v222, v223
	v_add_f32_e32 v241, v241, v243
	v_add_f32_e32 v150, v150, v241
	v_cvt_pk_bf16_f32 v208, v208, v209
	v_cvt_pk_bf16_f32 v209, v210, v211
	v_cvt_pk_bf16_f32 v210, v212, v213
	v_mfma_f32_16x16x32_bf16 v[28:31], v[92:95], v[120:123], v[28:31]
	v_cvt_pk_bf16_f32 v211, v214, v215
	v_cvt_pk_bf16_f32 v216, v216, v217
	v_cvt_pk_bf16_f32 v217, v218, v219
	v_cvt_pk_bf16_f32 v218, v220, v221
	v_cvt_pk_bf16_f32 v219, v222, v223
	s_nop 1
	v_mfma_f32_16x16x32_bf16 v[40:43], v[80:83], v[208:211], v[40:43]
	v_mfma_f32_16x16x32_bf16 v[12:15], v[80:83], v[216:219], v[12:15]
	v_mfma_f32_16x16x32_bf16 v[24:27], v[84:87], v[208:211], v[24:27]
	v_mfma_f32_16x16x32_bf16 v[8:11], v[84:87], v[216:219], v[8:11]
	v_mfma_f32_16x16x32_bf16 v[20:23], v[88:91], v[208:211], v[20:23]
	v_mfma_f32_16x16x32_bf16 v[0:3], v[88:91], v[216:219], v[0:3]
	v_mfma_f32_16x16x32_bf16 v[16:19], v[92:95], v[208:211], v[16:19]
	v_mfma_f32_16x16x32_bf16 v[4:7], v[92:95], v[216:219], v[4:7]
	s_branch .LBB0_65
.Lfoxf_fb0:
	v_sub_f32_e32 v112, v112, v244
	v_sub_f32_e32 v113, v113, v244
	v_sub_f32_e32 v114, v114, v244
	v_sub_f32_e32 v115, v115, v244
	v_sub_f32_e32 v116, v116, v244
	v_sub_f32_e32 v117, v117, v244
	v_sub_f32_e32 v118, v118, v244
	v_sub_f32_e32 v119, v119, v244
	v_sub_f32_e32 v120, v120, v245
	v_sub_f32_e32 v121, v121, v245
	v_sub_f32_e32 v122, v122, v245
	v_sub_f32_e32 v123, v123, v245
	v_sub_f32_e32 v124, v124, v245
	v_sub_f32_e32 v125, v125, v245
	v_sub_f32_e32 v126, v126, v245
	v_sub_f32_e32 v127, v127, v245
	v_add_f32_e32 v112, v112, v224
	v_add_f32_e32 v113, v113, v225
	v_add_f32_e32 v114, v114, v226
	v_add_f32_e32 v115, v115, v227
	v_add_f32_e32 v116, v116, v228
	v_add_f32_e32 v117, v117, v229
	v_add_f32_e32 v118, v118, v230
	v_add_f32_e32 v119, v119, v231
	v_add_f32_e32 v120, v120, v224
	v_add_f32_e32 v121, v121, v225
	v_add_f32_e32 v122, v122, v226
	v_add_f32_e32 v123, v123, v227
	v_add_f32_e32 v124, v124, v228
	v_add_f32_e32 v125, v125, v229
	v_add_f32_e32 v126, v126, v230
	v_add_f32_e32 v127, v127, v231
	s_branch .Lfoxf_x0
.Lfoxf_fb1:
	v_sub_f32_e32 v208, v208, v246
	v_sub_f32_e32 v209, v209, v246
	v_sub_f32_e32 v210, v210, v246
	v_sub_f32_e32 v211, v211, v246
	v_sub_f32_e32 v212, v212, v246
	v_sub_f32_e32 v213, v213, v246
	v_sub_f32_e32 v214, v214, v246
	v_sub_f32_e32 v215, v215, v246
	v_sub_f32_e32 v216, v216, v247
	v_sub_f32_e32 v217, v217, v247
	v_sub_f32_e32 v218, v218, v247
	v_sub_f32_e32 v219, v219, v247
	v_sub_f32_e32 v220, v220, v247
	v_sub_f32_e32 v221, v221, v247
	v_sub_f32_e32 v222, v222, v247
	v_sub_f32_e32 v223, v223, v247
	v_add_f32_e32 v208, v208, v224
	v_add_f32_e32 v209, v209, v225
	v_add_f32_e32 v210, v210, v226
	v_add_f32_e32 v211, v211, v227
	v_add_f32_e32 v212, v212, v228
	v_add_f32_e32 v213, v213, v229
	v_add_f32_e32 v214, v214, v230
	v_add_f32_e32 v215, v215, v231
	v_add_f32_e32 v216, v216, v224
	v_add_f32_e32 v217, v217, v225
	v_add_f32_e32 v218, v218, v226
	v_add_f32_e32 v219, v219, v227
	v_add_f32_e32 v220, v220, v228
	v_add_f32_e32 v221, v221, v229
	v_add_f32_e32 v222, v222, v230
	v_add_f32_e32 v223, v223, v231
	s_branch .Lfoxf_x1
.Lfoxf_fb2:
	v_sub_f32_e32 v112, v112, v244
	v_sub_f32_e32 v113, v113, v244
	v_sub_f32_e32 v114, v114, v244
	v_sub_f32_e32 v115, v115, v244
	v_sub_f32_e32 v116, v116, v244
	v_sub_f32_e32 v117, v117, v244
	v_sub_f32_e32 v118, v118, v244
	v_sub_f32_e32 v119, v119, v244
	v_sub_f32_e32 v120, v120, v245
	v_sub_f32_e32 v121, v121, v245
	v_sub_f32_e32 v122, v122, v245
	v_sub_f32_e32 v123, v123, v245
	v_sub_f32_e32 v124, v124, v245
	v_sub_f32_e32 v125, v125, v245
	v_sub_f32_e32 v126, v126, v245
	v_sub_f32_e32 v127, v127, v245
	v_add_f32_e32 v112, v112, v232
	v_add_f32_e32 v113, v113, v233
	v_add_f32_e32 v114, v114, v234
	v_add_f32_e32 v115, v115, v235
	v_add_f32_e32 v116, v116, v236
	v_add_f32_e32 v117, v117, v237
	v_add_f32_e32 v118, v118, v238
	v_add_f32_e32 v119, v119, v239
	v_add_f32_e32 v120, v120, v232
	v_add_f32_e32 v121, v121, v233
	v_add_f32_e32 v122, v122, v234
	v_add_f32_e32 v123, v123, v235
	v_add_f32_e32 v124, v124, v236
	v_add_f32_e32 v125, v125, v237
	v_add_f32_e32 v126, v126, v238
	v_add_f32_e32 v127, v127, v239
	s_branch .Lfoxf_x2
.Lfoxf_fb3:
	v_sub_f32_e32 v208, v208, v246
	v_sub_f32_e32 v209, v209, v246
	v_sub_f32_e32 v210, v210, v246
	v_sub_f32_e32 v211, v211, v246
	v_sub_f32_e32 v212, v212, v246
	v_sub_f32_e32 v213, v213, v246
	v_sub_f32_e32 v214, v214, v246
	v_sub_f32_e32 v215, v215, v246
	v_sub_f32_e32 v216, v216, v247
	v_sub_f32_e32 v217, v217, v247
	v_sub_f32_e32 v218, v218, v247
	v_sub_f32_e32 v219, v219, v247
	v_sub_f32_e32 v220, v220, v247
	v_sub_f32_e32 v221, v221, v247
	v_sub_f32_e32 v222, v222, v247
	v_sub_f32_e32 v223, v223, v247
	v_add_f32_e32 v208, v208, v232
	v_add_f32_e32 v209, v209, v233
	v_add_f32_e32 v210, v210, v234
	v_add_f32_e32 v211, v211, v235
	v_add_f32_e32 v212, v212, v236
	v_add_f32_e32 v213, v213, v237
	v_add_f32_e32 v214, v214, v238
	v_add_f32_e32 v215, v215, v239
	v_add_f32_e32 v216, v216, v232
	v_add_f32_e32 v217, v217, v233
	v_add_f32_e32 v218, v218, v234
	v_add_f32_e32 v219, v219, v235
	v_add_f32_e32 v220, v220, v236
	v_add_f32_e32 v221, v221, v237
	v_add_f32_e32 v222, v222, v238
	v_add_f32_e32 v223, v223, v239
	s_branch .Lfoxf_x3

.Lself_lazy:
	v_min3_f32 v134, v223, v222, v191
	v_min_f32_e32 v134, v134, v171
	v_cmp_gt_f32_e32 vcc, 0xefa18f08, v134
	s_nop 1
	s_cbranch_vccnz .Lself_fast
	v_add_u32_e32 v134, s10, v208
	v_add_u32_e32 v250, v134, v149
	v_add_u32_e32 v251, v134, v155
	v_add_u32_e32 v254, v147, v149
	v_add_u32_e32 v255, v147, v155
	v_add_u32_e32 v196, v134, v210
	v_add_u32_e32 v197, v134, v211
	v_add_u32_e32 v236, v134, v212
	v_add_u32_e32 v237, v134, v213
	ds_read_b128 v[64:67], v250
	ds_read_b128 v[68:71], v250 offset:2048
	ds_read_b128 v[72:75], v251
	ds_read_b128 v[76:79], v251 offset:2048
	ds_read_b128 v[98:101], v254 offset:32768
	ds_read_b128 v[102:105], v255 offset:32768
	ds_read_b128 v[106:109], v254 offset:40960
	ds_read_b128 v[110:113], v255 offset:40960
	ds_read_b64 v[80:81], v196 offset:8192
	ds_read_b64 v[82:83], v197 offset:8192
	ds_read_b64 v[84:85], v196 offset:10240
	ds_read_b64 v[86:87], v197 offset:10240
	ds_read_b64 v[90:91], v196 offset:12288
	ds_read_b64 v[92:93], v197 offset:12288
	ds_read_b64 v[94:95], v196 offset:14336
	ds_read_b64 v[96:97], v197 offset:14336
	v_lshrrev_b64 v[134:135], v88, v[172:173]
	v_and_b32_e32 v134, 1, v134
	v_cmp_eq_u32_e64 s[20:21], 1, v134
	s_nop 1
	v_cndmask_b32_e64 v89, v204, 0, s[20:21]
	v_cndmask_b32_e64 v238, v204, -v223, s[20:21]
	v_cndmask_b32_e64 v239, v204, -v223, s[20:21]
	v_cndmask_b32_e64 v240, v204, -v223, s[20:21]
	v_cndmask_b32_e64 v241, v204, -v223, s[20:21]
	v_cndmask_b32_e64 v242, v204, -v222, s[20:21]
	v_cndmask_b32_e64 v243, v204, -v222, s[20:21]
	v_cndmask_b32_e64 v244, v204, -v222, s[20:21]
	v_cndmask_b32_e64 v245, v204, -v222, s[20:21]
	v_cndmask_b32_e64 v246, v204, -v191, s[20:21]
	v_cndmask_b32_e64 v247, v204, -v191, s[20:21]
	v_cndmask_b32_e64 v248, v204, -v191, s[20:21]
	v_cndmask_b32_e64 v249, v204, -v191, s[20:21]
	v_cndmask_b32_e64 v192, v204, -v171, s[20:21]
	v_cndmask_b32_e64 v193, v204, -v171, s[20:21]
	v_cndmask_b32_e64 v194, v204, -v171, s[20:21]
	v_cndmask_b32_e64 v195, v204, -v171, s[20:21]
	s_waitcnt lgkmcnt(8)
	v_mfma_f32_16x16x32_bf16 v[114:117], v[64:67], v[98:101], v[238:241]
	v_mfma_f32_16x16x32_bf16 v[118:121], v[68:71], v[98:101], v[238:241]
	v_mfma_f32_16x16x32_bf16 v[122:125], v[64:67], v[106:109], v[242:245]
	v_mfma_f32_16x16x32_bf16 v[126:129], v[68:71], v[106:109], v[242:245]
	v_mfma_f32_16x16x32_bf16 v[114:117], v[72:75], v[102:105], v[114:117]
	v_mfma_f32_16x16x32_bf16 v[118:121], v[76:79], v[102:105], v[118:121]
	v_mfma_f32_16x16x32_bf16 v[122:125], v[72:75], v[110:113], v[122:125]
	v_mfma_f32_16x16x32_bf16 v[126:129], v[76:79], v[110:113], v[126:129]
	ds_read_b128 v[98:101], v254 offset:49152
	ds_read_b128 v[102:105], v255 offset:49152
	ds_read_b128 v[106:109], v254 offset:57344
	ds_read_b128 v[110:113], v255 offset:57344
	s_nop 0
	v_max3_f32 v134, v114, s75, v115
	v_max3_f32 v134, v134, v116, v117
	v_max3_f32 v134, v134, v118, v119
	v_max3_f32 v134, v134, v120, v121
	v_max3_f32 v135, v122, s75, v123
	v_max3_f32 v135, v135, v124, v125
	v_max3_f32 v135, v135, v126, v127
	v_max3_f32 v135, v135, v128, v129
	v_max_f32_e32 v134, v134, v135
	v_cmp_lt_f32_e32 vcc, 0x41000000, v134
	s_nop 1
	s_cbranch_vccnz .Lself_fb0
	s_waitcnt lgkmcnt(0)
	v_mfma_f32_16x16x32_bf16 v[224:227], v[64:67], v[98:101], v[246:249]
	v_exp_f32_e32 v114, v114
	v_exp_f32_e32 v115, v115
	v_exp_f32_e32 v116, v116
	v_exp_f32_e32 v117, v117
	v_exp_f32_e32 v118, v118
	v_mfma_f32_16x16x32_bf16 v[228:231], v[68:71], v[98:101], v[246:249]
	v_exp_f32_e32 v119, v119
	v_exp_f32_e32 v120, v120
	v_exp_f32_e32 v121, v121
	v_exp_f32_e32 v122, v122
	v_exp_f32_e32 v123, v123
	v_mfma_f32_16x16x32_bf16 v[232:235], v[64:67], v[106:109], v[192:195]
	v_exp_f32_e32 v124, v124
	v_exp_f32_e32 v125, v125
	v_exp_f32_e32 v126, v126
	v_exp_f32_e32 v127, v127
	v_exp_f32_e32 v128, v128
	v_mfma_f32_16x16x32_bf16 v[130:133], v[68:71], v[106:109], v[192:195]
	v_exp_f32_e32 v129, v129
	v_add_f32_e32 v134, v114, v115
	v_add_f32_e32 v188, v116, v117
	v_add_f32_e32 v134, v134, v188
	v_add_f32_e32 v188, v118, v119
	v_mfma_f32_16x16x32_bf16 v[224:227], v[72:75], v[102:105], v[224:227]
	v_add_f32_e32 v134, v134, v188
	v_add_f32_e32 v188, v120, v121
	v_add_f32_e32 v134, v134, v188
	v_add_f32_e32 v185, v185, v134
	v_add_f32_e32 v135, v122, v123
	v_mfma_f32_16x16x32_bf16 v[228:231], v[76:79], v[102:105], v[228:231]
	v_add_f32_e32 v189, v124, v125
	v_add_f32_e32 v135, v135, v189
	v_add_f32_e32 v189, v126, v127
	v_add_f32_e32 v135, v135, v189
	v_add_f32_e32 v189, v128, v129
	v_mfma_f32_16x16x32_bf16 v[232:235], v[72:75], v[110:113], v[232:235]
	v_add_f32_e32 v135, v135, v189
	v_add_f32_e32 v184, v184, v135
	v_cvt_pk_bf16_f32 v114, v114, v115
	v_cvt_pk_bf16_f32 v115, v116, v117
	v_cvt_pk_bf16_f32 v116, v118, v119
	v_mfma_f32_16x16x32_bf16 v[130:133], v[76:79], v[110:113], v[130:133]
	ds_read_b128 v[64:67], v250 offset:4096
	ds_read_b128 v[68:71], v250 offset:6144
	ds_read_b128 v[72:75], v251 offset:4096
	ds_read_b128 v[76:79], v251 offset:6144
	ds_read_b128 v[98:101], v254 offset:32768
	ds_read_b128 v[102:105], v255 offset:32768
	ds_read_b128 v[106:109], v254 offset:40960
	ds_read_b128 v[110:113], v255 offset:40960
	v_cvt_pk_bf16_f32 v117, v120, v121
	v_cvt_pk_bf16_f32 v122, v122, v123
	v_cvt_pk_bf16_f32 v123, v124, v125
	v_cvt_pk_bf16_f32 v124, v126, v127
	v_cvt_pk_bf16_f32 v125, v128, v129
	s_waitcnt lgkmcnt(12)
	v_mfma_f32_16x16x32_bf16 v[60:63], v[80:83], v[114:117], v[60:63]
	v_max3_f32 v134, v224, s75, v225
	v_max3_f32 v134, v134, v226, v227
	v_max3_f32 v134, v134, v228, v229
	v_max3_f32 v134, v134, v230, v231
	v_max3_f32 v135, v232, s75, v233
	v_max3_f32 v135, v135, v234, v235
	v_max3_f32 v135, v135, v130, v131
	v_max3_f32 v135, v135, v132, v133
	v_max_f32_e32 v134, v134, v135
	v_cmp_lt_f32_e32 vcc, 0x41000000, v134
	s_nop 1
	s_cbranch_vccnz .Lself_fb1
	v_mfma_f32_16x16x32_bf16 v[44:47], v[80:83], v[122:125], v[44:47]
	v_exp_f32_e32 v224, v224
	v_exp_f32_e32 v225, v225
	v_exp_f32_e32 v226, v226
	v_mfma_f32_16x16x32_bf16 v[56:59], v[84:87], v[114:117], v[56:59]
	v_exp_f32_e32 v227, v227
	v_exp_f32_e32 v228, v228
	v_exp_f32_e32 v229, v229
	v_mfma_f32_16x16x32_bf16 v[28:31], v[84:87], v[122:125], v[28:31]
	v_exp_f32_e32 v230, v230
	v_exp_f32_e32 v231, v231
	v_mfma_f32_16x16x32_bf16 v[52:55], v[90:93], v[114:117], v[52:55]
	v_exp_f32_e32 v232, v232
	v_exp_f32_e32 v233, v233
	v_exp_f32_e32 v234, v234
	v_mfma_f32_16x16x32_bf16 v[32:35], v[90:93], v[122:125], v[32:35]
	v_exp_f32_e32 v235, v235
	v_exp_f32_e32 v130, v130
	v_exp_f32_e32 v131, v131
	v_mfma_f32_16x16x32_bf16 v[48:51], v[94:97], v[114:117], v[48:51]
	v_exp_f32_e32 v132, v132
	v_exp_f32_e32 v133, v133
	v_mfma_f32_16x16x32_bf16 v[24:27], v[94:97], v[122:125], v[24:27]
	v_add_f32_e32 v134, v224, v225
	v_add_f32_e32 v188, v226, v227
	v_add_f32_e32 v134, v134, v188
	s_waitcnt lgkmcnt(0)
	v_mfma_f32_16x16x32_bf16 v[114:117], v[64:67], v[98:101], v[238:241]
	v_add_f32_e32 v188, v228, v229
	v_add_f32_e32 v134, v134, v188
	v_add_f32_e32 v188, v230, v231
	v_mfma_f32_16x16x32_bf16 v[118:121], v[68:71], v[98:101], v[238:241]
	v_add_f32_e32 v134, v134, v188
	v_add_f32_e32 v187, v187, v134
	v_mfma_f32_16x16x32_bf16 v[122:125], v[64:67], v[106:109], v[242:245]
	v_add_f32_e32 v135, v232, v233
	v_add_f32_e32 v189, v234, v235
	v_add_f32_e32 v135, v135, v189
	v_mfma_f32_16x16x32_bf16 v[126:129], v[68:71], v[106:109], v[242:245]
	v_add_f32_e32 v189, v130, v131
	v_add_f32_e32 v135, v135, v189
	v_add_f32_e32 v189, v132, v133
	v_mfma_f32_16x16x32_bf16 v[114:117], v[72:75], v[102:105], v[114:117]
	v_add_f32_e32 v135, v135, v189
	v_add_f32_e32 v186, v186, v135
	v_mfma_f32_16x16x32_bf16 v[118:121], v[76:79], v[102:105], v[118:121]
	v_cvt_pk_bf16_f32 v224, v224, v225
	v_cvt_pk_bf16_f32 v225, v226, v227
	v_cvt_pk_bf16_f32 v226, v228, v229
	v_mfma_f32_16x16x32_bf16 v[122:125], v[72:75], v[110:113], v[122:125]
	v_cvt_pk_bf16_f32 v227, v230, v231
	v_cvt_pk_bf16_f32 v232, v232, v233
	v_cvt_pk_bf16_f32 v233, v234, v235
	v_mfma_f32_16x16x32_bf16 v[126:129], v[76:79], v[110:113], v[126:129]
	ds_read_b128 v[98:101], v254 offset:49152
	ds_read_b128 v[102:105], v255 offset:49152
	ds_read_b128 v[106:109], v254 offset:57344
	ds_read_b128 v[110:113], v255 offset:57344
	v_cvt_pk_bf16_f32 v234, v130, v131
	v_cvt_pk_bf16_f32 v235, v132, v133
	v_mfma_f32_16x16x32_bf16 v[40:43], v[80:83], v[224:227], v[40:43]
	v_max3_f32 v134, v114, s75, v115
	v_max3_f32 v134, v134, v116, v117
	v_max3_f32 v134, v134, v118, v119
	v_max3_f32 v134, v134, v120, v121
	v_max3_f32 v135, v122, s75, v123
	v_max3_f32 v135, v135, v124, v125
	v_max3_f32 v135, v135, v126, v127
	v_max3_f32 v135, v135, v128, v129
	v_max_f32_e32 v134, v134, v135
	v_cmp_lt_f32_e32 vcc, 0x41000000, v134
	s_nop 1
	s_cbranch_vccnz .Lself_fb2
	v_mfma_f32_16x16x32_bf16 v[12:15], v[80:83], v[232:235], v[12:15]
	v_exp_f32_e32 v114, v114
	v_exp_f32_e32 v115, v115
	v_exp_f32_e32 v116, v116
	v_mfma_f32_16x16x32_bf16 v[36:39], v[84:87], v[224:227], v[36:39]
	v_exp_f32_e32 v117, v117
	v_exp_f32_e32 v118, v118
	v_exp_f32_e32 v119, v119
	v_mfma_f32_16x16x32_bf16 v[8:11], v[84:87], v[232:235], v[8:11]
	v_exp_f32_e32 v120, v120
	v_exp_f32_e32 v121, v121
	v_mfma_f32_16x16x32_bf16 v[20:23], v[90:93], v[224:227], v[20:23]
	v_exp_f32_e32 v122, v122
	v_exp_f32_e32 v123, v123
	v_exp_f32_e32 v124, v124
	v_mfma_f32_16x16x32_bf16 v[4:7], v[90:93], v[232:235], v[4:7]
	v_exp_f32_e32 v125, v125
	v_exp_f32_e32 v126, v126
	v_exp_f32_e32 v127, v127
	v_mfma_f32_16x16x32_bf16 v[16:19], v[94:97], v[224:227], v[16:19]
	v_exp_f32_e32 v128, v128
	v_exp_f32_e32 v129, v129
	v_mfma_f32_16x16x32_bf16 v[0:3], v[94:97], v[232:235], v[0:3]
	v_add_f32_e32 v134, v114, v115
	v_add_f32_e32 v188, v116, v117
	v_add_f32_e32 v134, v134, v188
	ds_read_b64 v[80:81], v236 offset:8192
	ds_read_b64 v[82:83], v237 offset:8192
	ds_read_b64 v[84:85], v236 offset:10240
	ds_read_b64 v[86:87], v237 offset:10240
	ds_read_b64 v[90:91], v236 offset:12288
	ds_read_b64 v[92:93], v237 offset:12288
	ds_read_b64 v[94:95], v236 offset:14336
	ds_read_b64 v[96:97], v237 offset:14336
	s_waitcnt lgkmcnt(8)
	v_mfma_f32_16x16x32_bf16 v[224:227], v[64:67], v[98:101], v[246:249]
	v_add_f32_e32 v188, v118, v119
	v_add_f32_e32 v134, v134, v188
	v_add_f32_e32 v188, v120, v121
	v_mfma_f32_16x16x32_bf16 v[228:231], v[68:71], v[98:101], v[246:249]
	v_add_f32_e32 v134, v134, v188
	v_add_f32_e32 v185, v185, v134
	v_mfma_f32_16x16x32_bf16 v[232:235], v[64:67], v[106:109], v[192:195]
	v_add_f32_e32 v135, v122, v123
	v_add_f32_e32 v189, v124, v125
	v_add_f32_e32 v135, v135, v189
	v_mfma_f32_16x16x32_bf16 v[130:133], v[68:71], v[106:109], v[192:195]
	v_add_f32_e32 v189, v126, v127
	v_add_f32_e32 v135, v135, v189
	v_add_f32_e32 v189, v128, v129
	v_mfma_f32_16x16x32_bf16 v[224:227], v[72:75], v[102:105], v[224:227]
	v_add_f32_e32 v135, v135, v189
	v_add_f32_e32 v184, v184, v135
	v_mfma_f32_16x16x32_bf16 v[228:231], v[76:79], v[102:105], v[228:231]
	v_cvt_pk_bf16_f32 v114, v114, v115
	v_cvt_pk_bf16_f32 v115, v116, v117
	v_cvt_pk_bf16_f32 v116, v118, v119
	v_mfma_f32_16x16x32_bf16 v[232:235], v[72:75], v[110:113], v[232:235]
	v_cvt_pk_bf16_f32 v117, v120, v121
	v_cvt_pk_bf16_f32 v122, v122, v123
	v_cvt_pk_bf16_f32 v123, v124, v125
	v_mfma_f32_16x16x32_bf16 v[130:133], v[76:79], v[110:113], v[130:133]
	v_cvt_pk_bf16_f32 v124, v126, v127
	v_cvt_pk_bf16_f32 v125, v128, v129
	s_waitcnt lgkmcnt(0)
	v_mfma_f32_16x16x32_bf16 v[60:63], v[80:83], v[114:117], v[60:63]
	v_max3_f32 v134, v224, s75, v225
	v_max3_f32 v134, v134, v226, v227
	v_max3_f32 v134, v134, v228, v229
	v_max3_f32 v134, v134, v230, v231
	v_max3_f32 v135, v232, s75, v233
	v_max3_f32 v135, v135, v234, v235
	v_max3_f32 v135, v135, v130, v131
	v_max3_f32 v135, v135, v132, v133
	v_max_f32_e32 v134, v134, v135
	v_cmp_lt_f32_e32 vcc, 0x41000000, v134
	s_nop 1
	s_cbranch_vccnz .Lself_fb3
	v_mfma_f32_16x16x32_bf16 v[44:47], v[80:83], v[122:125], v[44:47]
	v_exp_f32_e32 v224, v224
	v_exp_f32_e32 v225, v225
	v_exp_f32_e32 v226, v226
	v_exp_f32_e32 v227, v227
	v_exp_f32_e32 v228, v228
	v_exp_f32_e32 v229, v229
	v_mfma_f32_16x16x32_bf16 v[56:59], v[84:87], v[114:117], v[56:59]
	v_exp_f32_e32 v230, v230
	v_exp_f32_e32 v231, v231
	v_exp_f32_e32 v232, v232
	v_exp_f32_e32 v233, v233
	v_exp_f32_e32 v234, v234
	v_exp_f32_e32 v235, v235
	v_mfma_f32_16x16x32_bf16 v[28:31], v[84:87], v[122:125], v[28:31]
	v_exp_f32_e32 v130, v130
	v_exp_f32_e32 v131, v131
	v_exp_f32_e32 v132, v132
	v_exp_f32_e32 v133, v133
	v_add_f32_e32 v134, v224, v225
	v_add_f32_e32 v188, v226, v227
	v_mfma_f32_16x16x32_bf16 v[52:55], v[90:93], v[114:117], v[52:55]
	v_add_f32_e32 v134, v134, v188
	v_add_f32_e32 v188, v228, v229
	v_add_f32_e32 v134, v134, v188
	v_add_f32_e32 v188, v230, v231
	v_add_f32_e32 v134, v134, v188
	v_mfma_f32_16x16x32_bf16 v[32:35], v[90:93], v[122:125], v[32:35]
	v_add_f32_e32 v187, v187, v134
	v_add_f32_e32 v135, v232, v233
	v_add_f32_e32 v189, v234, v235
	v_add_f32_e32 v135, v135, v189
	v_add_f32_e32 v189, v130, v131
	v_add_f32_e32 v135, v135, v189
	v_mfma_f32_16x16x32_bf16 v[48:51], v[94:97], v[114:117], v[48:51]
	v_add_f32_e32 v189, v132, v133
	v_add_f32_e32 v135, v135, v189
	v_add_f32_e32 v186, v186, v135
	v_cvt_pk_bf16_f32 v224, v224, v225
	v_cvt_pk_bf16_f32 v225, v226, v227
	v_cvt_pk_bf16_f32 v226, v228, v229
	v_mfma_f32_16x16x32_bf16 v[24:27], v[94:97], v[122:125], v[24:27]
	v_cvt_pk_bf16_f32 v227, v230, v231
	v_cvt_pk_bf16_f32 v232, v232, v233
	v_cvt_pk_bf16_f32 v233, v234, v235
	v_cvt_pk_bf16_f32 v234, v130, v131
	v_cvt_pk_bf16_f32 v235, v132, v133
	s_nop 1
	v_mfma_f32_16x16x32_bf16 v[40:43], v[80:83], v[224:227], v[40:43]
	v_mfma_f32_16x16x32_bf16 v[12:15], v[80:83], v[232:235], v[12:15]
	v_mfma_f32_16x16x32_bf16 v[36:39], v[84:87], v[224:227], v[36:39]
	v_mfma_f32_16x16x32_bf16 v[8:11], v[84:87], v[232:235], v[8:11]
	v_mfma_f32_16x16x32_bf16 v[20:23], v[90:93], v[224:227], v[20:23]
	v_mfma_f32_16x16x32_bf16 v[4:7], v[90:93], v[232:235], v[4:7]
	v_mfma_f32_16x16x32_bf16 v[16:19], v[94:97], v[224:227], v[16:19]
	v_mfma_f32_16x16x32_bf16 v[0:3], v[94:97], v[232:235], v[0:3]
	s_waitcnt lgkmcnt(0)
	s_waitcnt vmcnt(0)
	s_barrier
	s_andn2_b64 vcc, exec, s[4:5]
	s_cmp_lg_u64 s[6:7], 0
	s_cselect_b32 s6, 1, 0
	s_xor_b32 s42, s42, s6
	s_cbranch_vccz .LBB0_107
	s_branch .Lself_latch

.Lwinf_go:
	v_min3_f32 v84, v184, v182, v170
	v_min_f32_e32 v84, v84, v188
	v_cmp_gt_f32_e32 vcc, 0xefa18f08, v84
	s_nop 1
	s_cbranch_vccnz .Lwinf_ex
	v_add_u32_e32 v134, s10, v208
	v_add_u32_e32 v250, v134, v149
	v_add_u32_e32 v251, v134, v155
	v_add_u32_e32 v254, v147, v149
	v_add_u32_e32 v255, v147, v155
	v_add_u32_e32 v194, v134, v210
	v_add_u32_e32 v195, v134, v211
	v_add_u32_e32 v196, v134, v212
	v_add_u32_e32 v197, v134, v213
	ds_read_b128 v[52:55], v250
	ds_read_b128 v[56:59], v250 offset:2048
	ds_read_b128 v[60:63], v251
	ds_read_b128 v[64:67], v251 offset:2048
	ds_read_b128 v[104:107], v254 offset:32768
	ds_read_b128 v[108:111], v255 offset:32768
	ds_read_b128 v[112:115], v254 offset:40960
	ds_read_b128 v[116:119], v255 offset:40960
	ds_read_b64 v[68:69], v194 offset:8192
	ds_read_b64 v[70:71], v195 offset:8192
	ds_read_b64 v[72:73], v194 offset:10240
	ds_read_b64 v[74:75], v195 offset:10240
	ds_read_b64 v[76:77], v194 offset:12288
	ds_read_b64 v[78:79], v195 offset:12288
	ds_read_b64 v[80:81], v194 offset:14336
	ds_read_b64 v[82:83], v195 offset:14336
	v_sub_f32_e32 v224, 0, v184
	v_sub_f32_e32 v225, 0, v184
	v_sub_f32_e32 v226, 0, v184
	v_sub_f32_e32 v227, 0, v184
	v_sub_f32_e32 v228, 0, v182
	v_sub_f32_e32 v229, 0, v182
	v_sub_f32_e32 v230, 0, v182
	v_sub_f32_e32 v231, 0, v182
	v_sub_f32_e32 v232, 0, v170
	v_sub_f32_e32 v233, 0, v170
	v_sub_f32_e32 v234, 0, v170
	v_sub_f32_e32 v235, 0, v170
	v_sub_f32_e32 v246, 0, v188
	v_sub_f32_e32 v247, 0, v188
	v_sub_f32_e32 v248, 0, v188
	v_sub_f32_e32 v249, 0, v188
	s_waitcnt lgkmcnt(8)
	v_mfma_f32_16x16x32_bf16 v[120:123], v[52:55], v[104:107], v[224:227]
	v_mfma_f32_16x16x32_bf16 v[124:127], v[56:59], v[104:107], v[224:227]
	v_mfma_f32_16x16x32_bf16 v[128:131], v[52:55], v[112:115], v[228:231]
	v_mfma_f32_16x16x32_bf16 v[172:175], v[56:59], v[112:115], v[228:231]
	v_mfma_f32_16x16x32_bf16 v[120:123], v[60:63], v[108:111], v[120:123]
	v_mfma_f32_16x16x32_bf16 v[124:127], v[64:67], v[108:111], v[124:127]
	v_mfma_f32_16x16x32_bf16 v[128:131], v[60:63], v[116:119], v[128:131]
	v_mfma_f32_16x16x32_bf16 v[172:175], v[64:67], v[116:119], v[172:175]
	ds_read_b128 v[104:107], v254 offset:49152
	ds_read_b128 v[108:111], v255 offset:49152
	ds_read_b128 v[112:115], v254 offset:57344
	ds_read_b128 v[116:119], v255 offset:57344
	s_nop 0
	v_max3_f32 v84, v120, s75, v121
	v_max3_f32 v84, v84, v122, v123
	v_max3_f32 v84, v84, v124, v125
	v_max3_f32 v84, v84, v126, v127
	v_max3_f32 v85, v128, s75, v129
	v_max3_f32 v85, v85, v130, v131
	v_max3_f32 v85, v85, v172, v173
	v_max3_f32 v85, v85, v174, v175
	v_max_f32_e32 v84, v84, v85
	v_cmp_lt_f32_e32 vcc, 0x41000000, v84
	s_nop 1
	s_cbranch_vccnz .Lwinf_fb0
	s_waitcnt lgkmcnt(0)
	v_mfma_f32_16x16x32_bf16 v[176:179], v[52:55], v[104:107], v[232:235]
	v_exp_f32_e32 v120, v120
	v_exp_f32_e32 v121, v121
	v_exp_f32_e32 v122, v122
	v_exp_f32_e32 v123, v123
	v_exp_f32_e32 v124, v124
	v_mfma_f32_16x16x32_bf16 v[190:193], v[56:59], v[104:107], v[232:235]
	v_exp_f32_e32 v125, v125
	v_exp_f32_e32 v126, v126
	v_exp_f32_e32 v127, v127
	v_exp_f32_e32 v128, v128
	v_exp_f32_e32 v129, v129
	v_mfma_f32_16x16x32_bf16 v[238:241], v[52:55], v[112:115], v[246:249]
	v_exp_f32_e32 v130, v130
	v_exp_f32_e32 v131, v131
	v_exp_f32_e32 v172, v172
	v_exp_f32_e32 v173, v173
	v_exp_f32_e32 v174, v174
	v_mfma_f32_16x16x32_bf16 v[242:245], v[56:59], v[112:115], v[246:249]
	v_exp_f32_e32 v175, v175
	v_add_f32_e32 v84, v120, v121
	v_add_f32_e32 v86, v122, v123
	v_add_f32_e32 v84, v84, v86
	v_add_f32_e32 v86, v124, v125
	v_mfma_f32_16x16x32_bf16 v[176:179], v[60:63], v[108:111], v[176:179]
	v_add_f32_e32 v84, v84, v86
	v_add_f32_e32 v86, v126, v127
	v_add_f32_e32 v84, v84, v86
	v_add_f32_e32 v133, v133, v84
	v_add_f32_e32 v85, v128, v129
	v_mfma_f32_16x16x32_bf16 v[190:193], v[64:67], v[108:111], v[190:193]
	v_add_f32_e32 v87, v130, v131
	v_add_f32_e32 v85, v85, v87
	v_add_f32_e32 v87, v172, v173
	v_add_f32_e32 v85, v85, v87
	v_add_f32_e32 v87, v174, v175
	v_mfma_f32_16x16x32_bf16 v[238:241], v[60:63], v[116:119], v[238:241]
	v_add_f32_e32 v85, v85, v87
	v_add_f32_e32 v132, v132, v85
	v_cvt_pk_bf16_f32 v120, v120, v121
	v_cvt_pk_bf16_f32 v121, v122, v123
	v_cvt_pk_bf16_f32 v122, v124, v125
	v_mfma_f32_16x16x32_bf16 v[242:245], v[64:67], v[116:119], v[242:245]
	ds_read_b128 v[52:55], v250 offset:4096
	ds_read_b128 v[56:59], v250 offset:6144
	ds_read_b128 v[60:63], v251 offset:4096
	ds_read_b128 v[64:67], v251 offset:6144
	ds_read_b128 v[104:107], v254 offset:32768
	ds_read_b128 v[108:111], v255 offset:32768
	ds_read_b128 v[112:115], v254 offset:40960
	ds_read_b128 v[116:119], v255 offset:40960
	v_cvt_pk_bf16_f32 v123, v126, v127
	v_cvt_pk_bf16_f32 v128, v128, v129
	v_cvt_pk_bf16_f32 v129, v130, v131
	v_cvt_pk_bf16_f32 v130, v172, v173
	v_cvt_pk_bf16_f32 v131, v174, v175
	s_waitcnt lgkmcnt(12)
	v_mfma_f32_16x16x32_bf16 v[100:103], v[68:71], v[120:123], v[100:103]
	v_max3_f32 v84, v176, s75, v177
	v_max3_f32 v84, v84, v178, v179
	v_max3_f32 v84, v84, v190, v191
	v_max3_f32 v84, v84, v192, v193
	v_max3_f32 v85, v238, s75, v239
	v_max3_f32 v85, v85, v240, v241
	v_max3_f32 v85, v85, v242, v243
	v_max3_f32 v85, v85, v244, v245
	v_max_f32_e32 v84, v84, v85
	v_cmp_lt_f32_e32 vcc, 0x41000000, v84
	s_nop 1
	s_cbranch_vccnz .Lwinf_fb1
	v_mfma_f32_16x16x32_bf16 v[36:39], v[68:71], v[128:131], v[36:39]
	v_exp_f32_e32 v176, v176
	v_exp_f32_e32 v177, v177
	v_exp_f32_e32 v178, v178
	v_mfma_f32_16x16x32_bf16 v[96:99], v[72:75], v[120:123], v[96:99]
	v_exp_f32_e32 v179, v179
	v_exp_f32_e32 v190, v190
	v_exp_f32_e32 v191, v191
	v_mfma_f32_16x16x32_bf16 v[32:35], v[72:75], v[128:131], v[32:35]
	v_exp_f32_e32 v192, v192
	v_exp_f32_e32 v193, v193
	v_mfma_f32_16x16x32_bf16 v[92:95], v[76:79], v[120:123], v[92:95]
	v_exp_f32_e32 v238, v238
	v_exp_f32_e32 v239, v239
	v_exp_f32_e32 v240, v240
	v_mfma_f32_16x16x32_bf16 v[28:31], v[76:79], v[128:131], v[28:31]
	v_exp_f32_e32 v241, v241
	v_exp_f32_e32 v242, v242
	v_exp_f32_e32 v243, v243
	v_mfma_f32_16x16x32_bf16 v[88:91], v[80:83], v[120:123], v[88:91]
	v_exp_f32_e32 v244, v244
	v_exp_f32_e32 v245, v245
	v_mfma_f32_16x16x32_bf16 v[24:27], v[80:83], v[128:131], v[24:27]
	v_add_f32_e32 v84, v176, v177
	v_add_f32_e32 v86, v178, v179
	v_add_f32_e32 v84, v84, v86
	s_waitcnt lgkmcnt(0)
	v_mfma_f32_16x16x32_bf16 v[120:123], v[52:55], v[104:107], v[224:227]
	v_add_f32_e32 v86, v190, v191
	v_add_f32_e32 v84, v84, v86
	v_add_f32_e32 v86, v192, v193
	v_mfma_f32_16x16x32_bf16 v[124:127], v[56:59], v[104:107], v[224:227]
	v_add_f32_e32 v84, v84, v86
	v_add_f32_e32 v165, v165, v84
	v_mfma_f32_16x16x32_bf16 v[128:131], v[52:55], v[112:115], v[228:231]
	v_add_f32_e32 v85, v238, v239
	v_add_f32_e32 v87, v240, v241
	v_add_f32_e32 v85, v85, v87
	v_mfma_f32_16x16x32_bf16 v[172:175], v[56:59], v[112:115], v[228:231]
	v_add_f32_e32 v87, v242, v243
	v_add_f32_e32 v85, v85, v87
	v_add_f32_e32 v87, v244, v245
	v_mfma_f32_16x16x32_bf16 v[120:123], v[60:63], v[108:111], v[120:123]
	v_add_f32_e32 v85, v85, v87
	v_add_f32_e32 v164, v164, v85
	v_mfma_f32_16x16x32_bf16 v[124:127], v[64:67], v[108:111], v[124:127]
	v_cvt_pk_bf16_f32 v176, v176, v177
	v_cvt_pk_bf16_f32 v177, v178, v179
	v_cvt_pk_bf16_f32 v178, v190, v191
	v_mfma_f32_16x16x32_bf16 v[128:131], v[60:63], v[116:119], v[128:131]
	v_cvt_pk_bf16_f32 v179, v192, v193
	v_cvt_pk_bf16_f32 v238, v238, v239
	v_cvt_pk_bf16_f32 v239, v240, v241
	v_mfma_f32_16x16x32_bf16 v[172:175], v[64:67], v[116:119], v[172:175]
	ds_read_b128 v[104:107], v254 offset:49152
	ds_read_b128 v[108:111], v255 offset:49152
	ds_read_b128 v[112:115], v254 offset:57344
	ds_read_b128 v[116:119], v255 offset:57344
	v_cvt_pk_bf16_f32 v240, v242, v243
	v_cvt_pk_bf16_f32 v241, v244, v245
	v_mfma_f32_16x16x32_bf16 v[44:47], v[68:71], v[176:179], v[44:47]
	v_max3_f32 v84, v120, s75, v121
	v_max3_f32 v84, v84, v122, v123
	v_max3_f32 v84, v84, v124, v125
	v_max3_f32 v84, v84, v126, v127
	v_max3_f32 v85, v128, s75, v129
	v_max3_f32 v85, v85, v130, v131
	v_max3_f32 v85, v85, v172, v173
	v_max3_f32 v85, v85, v174, v175
	v_max_f32_e32 v84, v84, v85
	v_cmp_lt_f32_e32 vcc, 0x41000000, v84
	s_nop 1
	s_cbranch_vccnz .Lwinf_fb2
	v_mfma_f32_16x16x32_bf16 v[12:15], v[68:71], v[238:241], v[12:15]
	v_exp_f32_e32 v120, v120
	v_exp_f32_e32 v121, v121
	v_exp_f32_e32 v122, v122
	v_mfma_f32_16x16x32_bf16 v[40:43], v[72:75], v[176:179], v[40:43]
	v_exp_f32_e32 v123, v123
	v_exp_f32_e32 v124, v124
	v_exp_f32_e32 v125, v125
	v_mfma_f32_16x16x32_bf16 v[8:11], v[72:75], v[238:241], v[8:11]
	v_exp_f32_e32 v126, v126
	v_exp_f32_e32 v127, v127
	v_mfma_f32_16x16x32_bf16 v[20:23], v[76:79], v[176:179], v[20:23]
	v_exp_f32_e32 v128, v128
	v_exp_f32_e32 v129, v129
	v_exp_f32_e32 v130, v130
	v_mfma_f32_16x16x32_bf16 v[4:7], v[76:79], v[238:241], v[4:7]
	v_exp_f32_e32 v131, v131
	v_exp_f32_e32 v172, v172
	v_exp_f32_e32 v173, v173
	v_mfma_f32_16x16x32_bf16 v[16:19], v[80:83], v[176:179], v[16:19]
	v_exp_f32_e32 v174, v174
	v_exp_f32_e32 v175, v175
	v_mfma_f32_16x16x32_bf16 v[0:3], v[80:83], v[238:241], v[0:3]
	v_add_f32_e32 v84, v120, v121
	v_add_f32_e32 v86, v122, v123
	v_add_f32_e32 v84, v84, v86
	ds_read_b64 v[68:69], v196 offset:8192
	ds_read_b64 v[70:71], v197 offset:8192
	ds_read_b64 v[72:73], v196 offset:10240
	ds_read_b64 v[74:75], v197 offset:10240
	ds_read_b64 v[76:77], v196 offset:12288
	ds_read_b64 v[78:79], v197 offset:12288
	ds_read_b64 v[80:81], v196 offset:14336
	ds_read_b64 v[82:83], v197 offset:14336
	s_waitcnt lgkmcnt(8)
	v_mfma_f32_16x16x32_bf16 v[176:179], v[52:55], v[104:107], v[232:235]
	v_add_f32_e32 v86, v124, v125
	v_add_f32_e32 v84, v84, v86
	v_add_f32_e32 v86, v126, v127
	v_mfma_f32_16x16x32_bf16 v[190:193], v[56:59], v[104:107], v[232:235]
	v_add_f32_e32 v84, v84, v86
	v_add_f32_e32 v133, v133, v84
	v_mfma_f32_16x16x32_bf16 v[238:241], v[52:55], v[112:115], v[246:249]
	v_add_f32_e32 v85, v128, v129
	v_add_f32_e32 v87, v130, v131
	v_add_f32_e32 v85, v85, v87
	v_mfma_f32_16x16x32_bf16 v[242:245], v[56:59], v[112:115], v[246:249]
	v_add_f32_e32 v87, v172, v173
	v_add_f32_e32 v85, v85, v87
	v_add_f32_e32 v87, v174, v175
	v_mfma_f32_16x16x32_bf16 v[176:179], v[60:63], v[108:111], v[176:179]
	v_add_f32_e32 v85, v85, v87
	v_add_f32_e32 v132, v132, v85
	v_mfma_f32_16x16x32_bf16 v[190:193], v[64:67], v[108:111], v[190:193]
	v_cvt_pk_bf16_f32 v120, v120, v121
	v_cvt_pk_bf16_f32 v121, v122, v123
	v_cvt_pk_bf16_f32 v122, v124, v125
	v_mfma_f32_16x16x32_bf16 v[238:241], v[60:63], v[116:119], v[238:241]
	v_cvt_pk_bf16_f32 v123, v126, v127
	v_cvt_pk_bf16_f32 v128, v128, v129
	v_cvt_pk_bf16_f32 v129, v130, v131
	v_mfma_f32_16x16x32_bf16 v[242:245], v[64:67], v[116:119], v[242:245]
	v_cvt_pk_bf16_f32 v130, v172, v173
	v_cvt_pk_bf16_f32 v131, v174, v175
	s_waitcnt lgkmcnt(0)
	v_mfma_f32_16x16x32_bf16 v[100:103], v[68:71], v[120:123], v[100:103]
	v_max3_f32 v84, v176, s75, v177
	v_max3_f32 v84, v84, v178, v179
	v_max3_f32 v84, v84, v190, v191
	v_max3_f32 v84, v84, v192, v193
	v_max3_f32 v85, v238, s75, v239
	v_max3_f32 v85, v85, v240, v241
	v_max3_f32 v85, v85, v242, v243
	v_max3_f32 v85, v85, v244, v245
	v_max_f32_e32 v84, v84, v85
	v_cmp_lt_f32_e32 vcc, 0x41000000, v84
	s_nop 1
	s_cbranch_vccnz .Lwinf_fb3
	v_mfma_f32_16x16x32_bf16 v[36:39], v[68:71], v[128:131], v[36:39]
	v_exp_f32_e32 v176, v176
	v_exp_f32_e32 v177, v177
	v_exp_f32_e32 v178, v178
	v_exp_f32_e32 v179, v179
	v_exp_f32_e32 v190, v190
	v_exp_f32_e32 v191, v191
	v_mfma_f32_16x16x32_bf16 v[96:99], v[72:75], v[120:123], v[96:99]
	v_exp_f32_e32 v192, v192
	v_exp_f32_e32 v193, v193
	v_exp_f32_e32 v238, v238
	v_exp_f32_e32 v239, v239
	v_exp_f32_e32 v240, v240
	v_exp_f32_e32 v241, v241
	v_mfma_f32_16x16x32_bf16 v[32:35], v[72:75], v[128:131], v[32:35]
	v_exp_f32_e32 v242, v242
	v_exp_f32_e32 v243, v243
	v_exp_f32_e32 v244, v244
	v_exp_f32_e32 v245, v245
	v_add_f32_e32 v84, v176, v177
	v_add_f32_e32 v86, v178, v179
	v_mfma_f32_16x16x32_bf16 v[92:95], v[76:79], v[120:123], v[92:95]
	v_add_f32_e32 v84, v84, v86
	v_add_f32_e32 v86, v190, v191
	v_add_f32_e32 v84, v84, v86
	v_add_f32_e32 v86, v192, v193
	v_add_f32_e32 v84, v84, v86
	v_mfma_f32_16x16x32_bf16 v[28:31], v[76:79], v[128:131], v[28:31]
	v_add_f32_e32 v165, v165, v84
	v_add_f32_e32 v85, v238, v239
	v_add_f32_e32 v87, v240, v241
	v_add_f32_e32 v85, v85, v87
	v_add_f32_e32 v87, v242, v243
	v_add_f32_e32 v85, v85, v87
	v_mfma_f32_16x16x32_bf16 v[88:91], v[80:83], v[120:123], v[88:91]
	v_add_f32_e32 v87, v244, v245
	v_add_f32_e32 v85, v85, v87
	v_add_f32_e32 v164, v164, v85
	v_cvt_pk_bf16_f32 v176, v176, v177
	v_cvt_pk_bf16_f32 v177, v178, v179
	v_cvt_pk_bf16_f32 v178, v190, v191
	v_mfma_f32_16x16x32_bf16 v[24:27], v[80:83], v[128:131], v[24:27]
	v_cvt_pk_bf16_f32 v179, v192, v193
	v_cvt_pk_bf16_f32 v238, v238, v239
	v_cvt_pk_bf16_f32 v239, v240, v241
	v_cvt_pk_bf16_f32 v240, v242, v243
	v_cvt_pk_bf16_f32 v241, v244, v245
	s_nop 1
	v_mfma_f32_16x16x32_bf16 v[44:47], v[68:71], v[176:179], v[44:47]
	v_mfma_f32_16x16x32_bf16 v[12:15], v[68:71], v[238:241], v[12:15]
	v_mfma_f32_16x16x32_bf16 v[40:43], v[72:75], v[176:179], v[40:43]
	v_mfma_f32_16x16x32_bf16 v[8:11], v[72:75], v[238:241], v[8:11]
	v_mfma_f32_16x16x32_bf16 v[20:23], v[76:79], v[176:179], v[20:23]
	v_mfma_f32_16x16x32_bf16 v[4:7], v[76:79], v[238:241], v[4:7]
	v_mfma_f32_16x16x32_bf16 v[16:19], v[80:83], v[176:179], v[16:19]
	v_mfma_f32_16x16x32_bf16 v[0:3], v[80:83], v[238:241], v[0:3]
	s_waitcnt lgkmcnt(0)
	s_waitcnt vmcnt(0)
	s_barrier
	s_andn2_b64 vcc, exec, s[4:5]
	s_cmp_lg_u64 s[6:7], 0
	s_cselect_b32 s6, 1, 0
	s_xor_b32 s84, s84, s6
	s_cbranch_vccz .LBB0_69
	s_branch .Lwinf_latch
